# C loop: loop-edge work folded into the MFMA stream and next-slot K fragments read inside the QK tail; GEMM K-loops: s_setprio 1 moved before the rendezvous, repeated lgkmcnt(0) dropped, s_setprio 0 mo
# speedup vs baseline: 1.0078x; 1.0078x over previous
; #define PG8_STAGE(bufoff, gbase, voff) do { _Pragma("unroll") for (int _i = 0; _i < 2; ++_i) \
;         __builtin_amdgcn_global_load_lds((const unsigned*)((const char*)(gbase) + (voff)[_i]), (PG8_LAS unsigned*)(lds + (bufoff) + ldsw + _i * 8192), 16, 0, 0); } while (0)
; #define PG8_LDA(dst, b, h) do { _Pragma("unroll") for (int m = 0; m < 4; ++m) _Pragma("unroll") for (int k = 0; k < 2; ++k) dst[m][k] = *(const PG8_LAS bf16x8*)(lds + PG8_SA(b, h) + aoff + m * 2048 + k * 1024); } while (0)
; #define PG8_LDB(dst, b, h) do { _Pragma("unroll") for (int n = 0; n < 2; ++n) _Pragma("unroll") for (int k = 0; k < 2; ++k) dst[n][k] = *(const PG8_LAS bf16x8*)(lds + PG8_SB(b, h) + boff + n * 2048 + k * 1024); } while (0)
; #define PG8_MMA(ai, bj, At, Bt) do { __builtin_amdgcn_s_setprio(1); _Pragma("unroll") for (int m = 0; m < 4; ++m) _Pragma("unroll") for (int n = 0; n < 2; ++n) _Pragma("unroll") for (int k = 0; k < 2; ++k) \
;         acc[ai][bj][m][n] = __builtin_amdgcn_mfma_f32_16x16x32_bf16(Bt[n][k], At[m][k], acc[ai][bj][m][n], 0, 0, 0); __builtin_amdgcn_s_setprio(0); } while (0)
; #define PG8_WAIT_V(n) asm volatile("s_waitcnt vmcnt(" #n ")" ::: "memory")
; #define PG8_WAIT_L(n) asm volatile("s_waitcnt lgkmcnt(" #n ")" ::: "memory")
; template <class Epi, class Sched, bool ALIGN_EPI = false, bool SP2 = false, class Hook = NoHook, bool REVK = false>
; __device__ __forceinline__ void gemm_phase(PG8_LAS unsigned char* lds, const Gemm g, const Sched& S, const Epi& E, const Hook H = Hook()) {
;     ...
;             const char* a1 = cA + (long)(t + 1) * kstep;
;             const char* a2 = last ? nA : cA + (long)(t + 2) * kstep; const char* b2 = last ? nB : cB + (long)(t + 2) * kstep;
;             const char* a3 = a2 + kstep; const char* b3 = b2 + kstep;
;             if (last && has_next) S.a_ready(nxt);
;             if constexpr (SP2) {
;             PG8_LDB(B0, 0, 0); PG8_LDB(B1, 0, 1); PG8_SCHED; PG8_LDA(At, 0, 0); PG8_STAGE(PG8_SA(1, 1), a1 + hstep, voffA);
;             PG8_WAIT_V(8); PG8_WAIT_L(0); PG8_BAR; PG8_MMA(0, 0, At, B0); PG8_MMA(0, 1, At, B1); PG8_BAR; PG8_SCHED;
;             PG8_LDA(At, 0, 1); PG8_STAGE(PG8_SB(0, 0), b2, voffB); PG8_STAGE(PG8_SB(0, 1), b2 + hstep, voffB); PG8_STAGE(PG8_SA(0, 0), a2, voffA);
;             PG8_WAIT_V(8); PG8_WAIT_L(0); PG8_BAR; PG8_MMA(1, 0, At, B0); PG8_MMA(1, 1, At, B1); PG8_BAR; PG8_SCHED;
.LBB0_59:
	s_add_u32 s20, s22, 0xfff80080
	s_addc_u32 s21, s23, -1
	s_add_i32 s46, 0, 0x10000
	s_cmp_eq_u32 s99, 28
	s_cselect_b32 s27, s29, s21
	s_cselect_b32 s26, s30, s20
	s_cselect_b32 s21, s31, s98
	s_cselect_b32 s20, s91, s93
	s_add_i32 s58, 0, 0x14000
	v_add_u32_e32 v108, s46, v164
	v_add_u32_e32 v128, s58, v164
	ds_read_b128 v[96:99], v108
	ds_read_b128 v[100:103], v108 offset:1024
	ds_read_b128 v[104:107], v108 offset:2048
	ds_read_b128 v[108:111], v108 offset:3072
	ds_read_b128 v[182:185], v128
	ds_read_b128 v[186:189], v128 offset:1024
	ds_read_b128 v[190:193], v128 offset:2048
	ds_read_b128 v[194:197], v128 offset:3072
	v_lshl_add_u64 v[162:163], s[22:23], 0, v[158:159]
	s_add_i32 m0, s43, 0xc000
	ds_read_b128 v[200:203], v167
	ds_read_b128 v[204:207], v167 offset:1024
	ds_read_b128 v[210:213], v167 offset:2048
	ds_read_b128 v[226:229], v167 offset:3072
	ds_read_b128 v[230:233], v167 offset:4096
	ds_read_b128 v[234:237], v167 offset:5120
	ds_read_b128 v[238:241], v167 offset:6144
	ds_read_b128 v[242:245], v167 offset:7168
	global_load_lds_dwordx4 v[162:163], off
	v_lshl_add_u64 v[162:163], s[22:23], 0, v[160:161]
	s_add_i32 m0, s43, 0xe000
	s_nop 0
	global_load_lds_dwordx4 v[162:163], off
	s_waitcnt vmcnt(8)
	s_waitcnt lgkmcnt(0)
	s_setprio 1
	s_barrier
	v_mfma_f32_16x16x32_bf16 v[142:145], v[96:99], v[200:203], v[142:145]
	v_mfma_f32_16x16x32_bf16 v[138:141], v[104:107], v[200:203], v[138:141]
	v_mfma_f32_16x16x32_bf16 v[116:119], v[96:99], v[210:213], v[116:119]
	v_mfma_f32_16x16x32_bf16 v[120:123], v[104:107], v[210:213], v[120:123]
	v_mfma_f32_16x16x32_bf16 v[84:87], v[96:99], v[230:233], v[84:87]
	v_mfma_f32_16x16x32_bf16 v[88:91], v[104:107], v[230:233], v[88:91]
	v_mfma_f32_16x16x32_bf16 v[68:71], v[96:99], v[238:241], v[68:71]
	v_mfma_f32_16x16x32_bf16 v[72:75], v[104:107], v[238:241], v[72:75]
	v_mfma_f32_16x16x32_bf16 v[142:145], v[100:103], v[204:207], v[142:145]
	v_mfma_f32_16x16x32_bf16 v[138:141], v[108:111], v[204:207], v[138:141]
	v_mfma_f32_16x16x32_bf16 v[116:119], v[100:103], v[226:229], v[116:119]
	v_mfma_f32_16x16x32_bf16 v[120:123], v[108:111], v[226:229], v[120:123]
	v_mfma_f32_16x16x32_bf16 v[84:87], v[100:103], v[234:237], v[84:87]
	v_mfma_f32_16x16x32_bf16 v[88:91], v[108:111], v[234:237], v[88:91]
	v_mfma_f32_16x16x32_bf16 v[68:71], v[100:103], v[242:245], v[68:71]
	v_mfma_f32_16x16x32_bf16 v[72:75], v[108:111], v[242:245], v[72:75]
	s_setprio 0
	s_setprio 1
	v_mfma_f32_16x16x32_bf16 v[130:133], v[182:185], v[200:203], v[130:133]
	v_mfma_f32_16x16x32_bf16 v[134:137], v[190:193], v[200:203], v[134:137]
	v_mfma_f32_16x16x32_bf16 v[112:115], v[182:185], v[210:213], v[112:115]
	v_mfma_f32_16x16x32_bf16 v[124:127], v[190:193], v[210:213], v[124:127]
	v_mfma_f32_16x16x32_bf16 v[80:83], v[182:185], v[230:233], v[80:83]
	v_mfma_f32_16x16x32_bf16 v[92:95], v[190:193], v[230:233], v[92:95]
	v_mfma_f32_16x16x32_bf16 v[64:67], v[182:185], v[238:241], v[64:67]
	v_mfma_f32_16x16x32_bf16 v[76:79], v[190:193], v[238:241], v[76:79]
	v_mfma_f32_16x16x32_bf16 v[130:133], v[186:189], v[204:207], v[130:133]
	v_mfma_f32_16x16x32_bf16 v[134:137], v[194:197], v[204:207], v[134:137]
	v_mfma_f32_16x16x32_bf16 v[112:115], v[186:189], v[226:229], v[112:115]
	v_mfma_f32_16x16x32_bf16 v[124:127], v[194:197], v[226:229], v[124:127]
	v_mfma_f32_16x16x32_bf16 v[80:83], v[186:189], v[234:237], v[80:83]
	v_mfma_f32_16x16x32_bf16 v[92:95], v[194:197], v[234:237], v[92:95]
	v_mfma_f32_16x16x32_bf16 v[64:67], v[186:189], v[242:245], v[64:67]
	v_mfma_f32_16x16x32_bf16 v[76:79], v[194:197], v[242:245], v[76:79]
	s_barrier
	s_setprio 0
	s_add_i32 s46, s46, s38
	v_lshl_add_u64 v[162:163], s[20:21], 0, v[150:151]
	s_mov_b32 m0, s46
	ds_read_b128 v[200:203], v167 offset:16384
	ds_read_b128 v[204:207], v167 offset:17408
	ds_read_b128 v[210:213], v167 offset:18432
	ds_read_b128 v[226:229], v167 offset:19456
	ds_read_b128 v[230:233], v167 offset:20480
	ds_read_b128 v[234:237], v167 offset:21504
	ds_read_b128 v[238:241], v167 offset:22528
	ds_read_b128 v[242:245], v167 offset:23552
	global_load_lds_dwordx4 v[162:163], off
	s_add_i32 m0, s46, 0x2000
	s_add_u32 s56, s20, 0x80000
	v_lshl_add_u64 v[168:169], s[20:21], 0, v[146:147]
	s_addc_u32 s57, s21, 0
	s_add_i32 s46, s58, s38
	global_load_lds_dwordx4 v[168:169], off
	v_lshl_add_u64 v[214:215], s[56:57], 0, v[150:151]
	s_mov_b32 m0, s46
	v_lshl_add_u64 v[246:247], s[26:27], 0, v[148:149]
	global_load_lds_dwordx4 v[214:215], off
	v_lshl_add_u64 v[214:215], s[56:57], 0, v[146:147]
	s_add_i32 m0, s46, 0x2000
	s_nop 0
	global_load_lds_dwordx4 v[214:215], off
	v_lshl_add_u64 v[214:215], s[26:27], 0, v[152:153]
	s_mov_b32 m0, s43
	s_nop 0
	global_load_lds_dwordx4 v[214:215], off
	s_mov_b32 m0, s75
	s_nop 0
	global_load_lds_dwordx4 v[246:247], off
	s_waitcnt vmcnt(8)
	s_waitcnt lgkmcnt(0)
	s_setprio 1
	s_barrier
; #define PG8_STAGE(bufoff, gbase, voff) do { _Pragma("unroll") for (int _i = 0; _i < 2; ++_i) \
;         __builtin_amdgcn_global_load_lds((const unsigned*)((const char*)(gbase) + (voff)[_i]), (PG8_LAS unsigned*)(lds + (bufoff) + ldsw + _i * 8192), 16, 0, 0); } while (0)
; #define PG8_LDA(dst, b, h) do { _Pragma("unroll") for (int m = 0; m < 4; ++m) _Pragma("unroll") for (int k = 0; k < 2; ++k) dst[m][k] = *(const PG8_LAS bf16x8*)(lds + PG8_SA(b, h) + aoff + m * 2048 + k * 1024); } while (0)
; #define PG8_LDB(dst, b, h) do { _Pragma("unroll") for (int n = 0; n < 2; ++n) _Pragma("unroll") for (int k = 0; k < 2; ++k) dst[n][k] = *(const PG8_LAS bf16x8*)(lds + PG8_SB(b, h) + boff + n * 2048 + k * 1024); } while (0)
; #define PG8_MMA(ai, bj, At, Bt) do { __builtin_amdgcn_s_setprio(1); _Pragma("unroll") for (int m = 0; m < 4; ++m) _Pragma("unroll") for (int n = 0; n < 2; ++n) _Pragma("unroll") for (int k = 0; k < 2; ++k) \
;         acc[ai][bj][m][n] = __builtin_amdgcn_mfma_f32_16x16x32_bf16(Bt[n][k], At[m][k], acc[ai][bj][m][n], 0, 0, 0); __builtin_amdgcn_s_setprio(0); } while (0)
; #define PG8_WAIT_V(n) asm volatile("s_waitcnt vmcnt(" #n ")" ::: "memory")
; #define PG8_WAIT_L(n) asm volatile("s_waitcnt lgkmcnt(" #n ")" ::: "memory")
; #define PG8_BAR __builtin_amdgcn_s_barrier()
; #define PG8_SCHED __builtin_amdgcn_sched_barrier(0)
; template <class Epi, class Sched, bool ALIGN_EPI = false, bool SP2 = false, class Hook = NoHook, bool REVK = false>
; __device__ __forceinline__ void gemm_phase(PG8_LAS unsigned char* lds, const Gemm g, const Sched& S, const Epi& E, const Hook H = Hook()) {
;     ...
;             PG8_WAIT_V(8); PG8_WAIT_L(0); PG8_BAR; PG8_MMA(1, 0, At, B0); PG8_MMA(1, 1, At, B1); PG8_BAR; PG8_SCHED;
;             PG8_LDB(B0, 1, 0); PG8_LDB(B1, 1, 1); PG8_SCHED; PG8_LDA(At, 1, 0); PG8_STAGE(PG8_SA(0, 1), a2 + hstep, voffA);
;             PG8_WAIT_V(8); PG8_WAIT_L(0); PG8_BAR; PG8_MMA(0, 0, At, B0); PG8_MMA(0, 1, At, B1); PG8_BAR; PG8_SCHED;
	v_mfma_f32_16x16x32_bf16 v[52:55], v[96:99], v[200:203], v[52:55]
	v_mfma_f32_16x16x32_bf16 v[56:59], v[104:107], v[200:203], v[56:59]
	v_mfma_f32_16x16x32_bf16 v[36:39], v[96:99], v[210:213], v[36:39]
	v_mfma_f32_16x16x32_bf16 v[40:43], v[104:107], v[210:213], v[40:43]
	v_mfma_f32_16x16x32_bf16 v[20:23], v[96:99], v[230:233], v[20:23]
	v_mfma_f32_16x16x32_bf16 v[24:27], v[104:107], v[230:233], v[24:27]
	v_mfma_f32_16x16x32_bf16 v[4:7], v[96:99], v[238:241], v[4:7]
	v_mfma_f32_16x16x32_bf16 v[8:11], v[104:107], v[238:241], v[8:11]
	v_mfma_f32_16x16x32_bf16 v[52:55], v[100:103], v[204:207], v[52:55]
	v_mfma_f32_16x16x32_bf16 v[56:59], v[108:111], v[204:207], v[56:59]
	v_mfma_f32_16x16x32_bf16 v[36:39], v[100:103], v[226:229], v[36:39]
	v_mfma_f32_16x16x32_bf16 v[40:43], v[108:111], v[226:229], v[40:43]
	v_mfma_f32_16x16x32_bf16 v[20:23], v[100:103], v[234:237], v[20:23]
	v_mfma_f32_16x16x32_bf16 v[24:27], v[108:111], v[234:237], v[24:27]
	v_mfma_f32_16x16x32_bf16 v[4:7], v[100:103], v[242:245], v[4:7]
	v_mfma_f32_16x16x32_bf16 v[8:11], v[108:111], v[242:245], v[8:11]
	s_setprio 0
	s_setprio 1
	v_mfma_f32_16x16x32_bf16 v[48:51], v[182:185], v[200:203], v[48:51]
	v_mfma_f32_16x16x32_bf16 v[60:63], v[190:193], v[200:203], v[60:63]
	v_mfma_f32_16x16x32_bf16 v[32:35], v[182:185], v[210:213], v[32:35]
	v_mfma_f32_16x16x32_bf16 v[44:47], v[190:193], v[210:213], v[44:47]
	v_mfma_f32_16x16x32_bf16 v[16:19], v[182:185], v[230:233], v[16:19]
	v_mfma_f32_16x16x32_bf16 v[28:31], v[190:193], v[230:233], v[28:31]
	v_mfma_f32_16x16x32_bf16 v[0:3], v[182:185], v[238:241], v[0:3]
	v_mfma_f32_16x16x32_bf16 v[12:15], v[190:193], v[238:241], v[12:15]
	v_mfma_f32_16x16x32_bf16 v[48:51], v[186:189], v[204:207], v[48:51]
	v_mfma_f32_16x16x32_bf16 v[60:63], v[194:197], v[204:207], v[60:63]
	v_mfma_f32_16x16x32_bf16 v[32:35], v[186:189], v[226:229], v[32:35]
	v_mfma_f32_16x16x32_bf16 v[44:47], v[194:197], v[226:229], v[44:47]
	v_mfma_f32_16x16x32_bf16 v[16:19], v[186:189], v[234:237], v[16:19]
	v_mfma_f32_16x16x32_bf16 v[28:31], v[194:197], v[234:237], v[28:31]
	v_mfma_f32_16x16x32_bf16 v[0:3], v[186:189], v[242:245], v[0:3]
	v_mfma_f32_16x16x32_bf16 v[12:15], v[194:197], v[242:245], v[12:15]
	s_barrier
	s_setprio 0
	s_add_i32 s46, 0, 0x18000
	s_add_i32 s56, 0, 0x1c000
	v_add_u32_e32 v108, s46, v164
	v_add_u32_e32 v128, s56, v164
	ds_read_b128 v[96:99], v108
	ds_read_b128 v[100:103], v108 offset:1024
	ds_read_b128 v[104:107], v108 offset:2048
	ds_read_b128 v[108:111], v108 offset:3072
	ds_read_b128 v[182:185], v128
	ds_read_b128 v[186:189], v128 offset:1024
	ds_read_b128 v[190:193], v128 offset:2048
	ds_read_b128 v[194:197], v128 offset:3072
	s_add_u32 s26, s26, 0x80000
	s_addc_u32 s27, s27, 0
	s_mov_b32 m0, s77
	v_lshl_add_u64 v[248:249], s[26:27], 0, v[152:153]
	ds_read_b128 v[200:203], v167 offset:32768
	ds_read_b128 v[204:207], v167 offset:33792
	ds_read_b128 v[210:213], v167 offset:34816
	ds_read_b128 v[226:229], v167 offset:35840
	ds_read_b128 v[230:233], v167 offset:36864
	ds_read_b128 v[234:237], v167 offset:37888
	ds_read_b128 v[238:241], v167 offset:38912
	ds_read_b128 v[242:245], v167 offset:39936
	global_load_lds_dwordx4 v[248:249], off
	v_lshl_add_u64 v[248:249], s[26:27], 0, v[148:149]
	s_mov_b32 m0, s79
	s_nop 0
	global_load_lds_dwordx4 v[248:249], off
	s_waitcnt vmcnt(8)
	s_waitcnt lgkmcnt(0)
	s_setprio 1
	s_barrier
	v_mfma_f32_16x16x32_bf16 v[142:145], v[96:99], v[200:203], v[142:145]
	v_mfma_f32_16x16x32_bf16 v[138:141], v[104:107], v[200:203], v[138:141]
	v_mfma_f32_16x16x32_bf16 v[116:119], v[96:99], v[210:213], v[116:119]
	v_mfma_f32_16x16x32_bf16 v[120:123], v[104:107], v[210:213], v[120:123]
	v_mfma_f32_16x16x32_bf16 v[84:87], v[96:99], v[230:233], v[84:87]
	v_mfma_f32_16x16x32_bf16 v[88:91], v[104:107], v[230:233], v[88:91]
	v_mfma_f32_16x16x32_bf16 v[68:71], v[96:99], v[238:241], v[68:71]
	v_mfma_f32_16x16x32_bf16 v[72:75], v[104:107], v[238:241], v[72:75]
	v_mfma_f32_16x16x32_bf16 v[142:145], v[100:103], v[204:207], v[142:145]
	v_mfma_f32_16x16x32_bf16 v[138:141], v[108:111], v[204:207], v[138:141]
	v_mfma_f32_16x16x32_bf16 v[116:119], v[100:103], v[226:229], v[116:119]
	v_mfma_f32_16x16x32_bf16 v[120:123], v[108:111], v[226:229], v[120:123]
	v_mfma_f32_16x16x32_bf16 v[84:87], v[100:103], v[234:237], v[84:87]
	v_mfma_f32_16x16x32_bf16 v[88:91], v[108:111], v[234:237], v[88:91]
	v_mfma_f32_16x16x32_bf16 v[68:71], v[100:103], v[242:245], v[68:71]
	v_mfma_f32_16x16x32_bf16 v[72:75], v[108:111], v[242:245], v[72:75]
	s_setprio 0
	s_setprio 1
	v_mfma_f32_16x16x32_bf16 v[130:133], v[182:185], v[200:203], v[130:133]
	v_mfma_f32_16x16x32_bf16 v[134:137], v[190:193], v[200:203], v[134:137]
	v_mfma_f32_16x16x32_bf16 v[112:115], v[182:185], v[210:213], v[112:115]
	v_mfma_f32_16x16x32_bf16 v[124:127], v[190:193], v[210:213], v[124:127]
	v_mfma_f32_16x16x32_bf16 v[80:83], v[182:185], v[230:233], v[80:83]
	v_mfma_f32_16x16x32_bf16 v[92:95], v[190:193], v[230:233], v[92:95]
	v_mfma_f32_16x16x32_bf16 v[64:67], v[182:185], v[238:241], v[64:67]
	v_mfma_f32_16x16x32_bf16 v[76:79], v[190:193], v[238:241], v[76:79]
	v_mfma_f32_16x16x32_bf16 v[130:133], v[186:189], v[204:207], v[130:133]
	v_mfma_f32_16x16x32_bf16 v[134:137], v[194:197], v[204:207], v[134:137]
	v_mfma_f32_16x16x32_bf16 v[112:115], v[186:189], v[226:229], v[112:115]
	v_mfma_f32_16x16x32_bf16 v[124:127], v[194:197], v[226:229], v[124:127]
	v_mfma_f32_16x16x32_bf16 v[80:83], v[186:189], v[234:237], v[80:83]
	v_mfma_f32_16x16x32_bf16 v[92:95], v[194:197], v[234:237], v[92:95]
	v_mfma_f32_16x16x32_bf16 v[64:67], v[186:189], v[242:245], v[64:67]
	v_mfma_f32_16x16x32_bf16 v[76:79], v[194:197], v[242:245], v[76:79]
	s_barrier
; #define PG8_STAGE(bufoff, gbase, voff) do { _Pragma("unroll") for (int _i = 0; _i < 2; ++_i) \
;         __builtin_amdgcn_global_load_lds((const unsigned*)((const char*)(gbase) + (voff)[_i]), (PG8_LAS unsigned*)(lds + (bufoff) + ldsw + _i * 8192), 16, 0, 0); } while (0)
; #define PG8_LDA(dst, b, h) do { _Pragma("unroll") for (int m = 0; m < 4; ++m) _Pragma("unroll") for (int k = 0; k < 2; ++k) dst[m][k] = *(const PG8_LAS bf16x8*)(lds + PG8_SA(b, h) + aoff + m * 2048 + k * 1024); } while (0)
; #define PG8_MMA(ai, bj, At, Bt) do { __builtin_amdgcn_s_setprio(1); _Pragma("unroll") for (int m = 0; m < 4; ++m) _Pragma("unroll") for (int n = 0; n < 2; ++n) _Pragma("unroll") for (int k = 0; k < 2; ++k) \
;         acc[ai][bj][m][n] = __builtin_amdgcn_mfma_f32_16x16x32_bf16(Bt[n][k], At[m][k], acc[ai][bj][m][n], 0, 0, 0); __builtin_amdgcn_s_setprio(0); } while (0)
; #define PG8_WAIT_V(n) asm volatile("s_waitcnt vmcnt(" #n ")" ::: "memory")
; #define PG8_WAIT_L(n) asm volatile("s_waitcnt lgkmcnt(" #n ")" ::: "memory")
; #define PG8_BAR __builtin_amdgcn_s_barrier()
; #define PG8_SCHED __builtin_amdgcn_sched_barrier(0)
; template <class Epi, class Sched, bool ALIGN_EPI = false, bool SP2 = false, class Hook = NoHook, bool REVK = false>
; __device__ __forceinline__ void gemm_phase(PG8_LAS unsigned char* lds, const Gemm g, const Sched& S, const Epi& E, const Hook H = Hook()) {
;     ...
;             PG8_WAIT_V(8); PG8_WAIT_L(0); PG8_BAR; PG8_MMA(0, 0, At, B0); PG8_MMA(0, 1, At, B1); PG8_BAR; PG8_SCHED;
;             PG8_LDA(At, 1, 1); PG8_STAGE(PG8_SB(1, 0), b3, voffB); PG8_STAGE(PG8_SB(1, 1), b3 + hstep, voffB); PG8_STAGE(PG8_SA(1, 0), a3, voffA);
;             PG8_WAIT_V(8); PG8_WAIT_L(0); PG8_BAR; PG8_MMA(1, 0, At, B0); PG8_MMA(1, 1, At, B1); PG8_BAR; PG8_SCHED;
	s_setprio 0
	s_add_i32 s26, s46, s38
	v_lshl_add_u64 v[162:163], v[162:163], 0, s[64:65]
	s_mov_b32 m0, s26
	ds_read_b128 v[200:203], v167 offset:49152
	ds_read_b128 v[204:207], v167 offset:50176
	ds_read_b128 v[210:213], v167 offset:51200
	ds_read_b128 v[226:229], v167 offset:52224
	ds_read_b128 v[230:233], v167 offset:53248
	ds_read_b128 v[234:237], v167 offset:54272
	ds_read_b128 v[238:241], v167 offset:55296
	ds_read_b128 v[242:245], v167 offset:56320
	global_load_lds_dwordx4 v[162:163], off
	s_add_i32 m0, s26, 0x2000
	s_add_u32 s20, s20, 0x80080
	v_lshl_add_u64 v[162:163], v[168:169], 0, s[64:65]
	s_addc_u32 s21, s21, 0
	s_add_i32 s26, s56, s38
	global_load_lds_dwordx4 v[162:163], off
	v_lshl_add_u64 v[162:163], s[20:21], 0, v[150:151]
	s_mov_b32 m0, s26
	s_nop 0
	global_load_lds_dwordx4 v[162:163], off
	v_lshl_add_u64 v[162:163], s[20:21], 0, v[146:147]
	s_add_i32 m0, s26, 0x2000
	s_nop 0
	global_load_lds_dwordx4 v[162:163], off
	v_lshl_add_u64 v[162:163], v[214:215], 0, s[64:65]
	s_mov_b32 m0, s44
	s_nop 0
	global_load_lds_dwordx4 v[162:163], off
	v_lshl_add_u64 v[162:163], v[246:247], 0, s[64:65]
	s_mov_b32 m0, s36
	s_nop 0
	global_load_lds_dwordx4 v[162:163], off
	s_waitcnt vmcnt(8)
	s_waitcnt lgkmcnt(0)
	s_setprio 1
	s_barrier
	v_mfma_f32_16x16x32_bf16 v[52:55], v[96:99], v[200:203], v[52:55]
	v_mfma_f32_16x16x32_bf16 v[56:59], v[104:107], v[200:203], v[56:59]
	v_mfma_f32_16x16x32_bf16 v[36:39], v[96:99], v[210:213], v[36:39]
	v_mfma_f32_16x16x32_bf16 v[40:43], v[104:107], v[210:213], v[40:43]
	v_mfma_f32_16x16x32_bf16 v[20:23], v[96:99], v[230:233], v[20:23]
	v_mfma_f32_16x16x32_bf16 v[24:27], v[104:107], v[230:233], v[24:27]
	v_mfma_f32_16x16x32_bf16 v[4:7], v[96:99], v[238:241], v[4:7]
	v_mfma_f32_16x16x32_bf16 v[8:11], v[104:107], v[238:241], v[8:11]
	v_mfma_f32_16x16x32_bf16 v[52:55], v[100:103], v[204:207], v[52:55]
	v_mfma_f32_16x16x32_bf16 v[56:59], v[108:111], v[204:207], v[56:59]
	v_mfma_f32_16x16x32_bf16 v[36:39], v[100:103], v[226:229], v[36:39]
	v_mfma_f32_16x16x32_bf16 v[40:43], v[108:111], v[226:229], v[40:43]
	v_mfma_f32_16x16x32_bf16 v[20:23], v[100:103], v[234:237], v[20:23]
	v_mfma_f32_16x16x32_bf16 v[24:27], v[108:111], v[234:237], v[24:27]
	v_mfma_f32_16x16x32_bf16 v[4:7], v[100:103], v[242:245], v[4:7]
	v_mfma_f32_16x16x32_bf16 v[8:11], v[108:111], v[242:245], v[8:11]
	s_setprio 0
	s_setprio 1
	v_mfma_f32_16x16x32_bf16 v[48:51], v[182:185], v[200:203], v[48:51]
	v_mfma_f32_16x16x32_bf16 v[60:63], v[190:193], v[200:203], v[60:63]
	v_mfma_f32_16x16x32_bf16 v[32:35], v[182:185], v[210:213], v[32:35]
	v_mfma_f32_16x16x32_bf16 v[44:47], v[190:193], v[210:213], v[44:47]
	v_mfma_f32_16x16x32_bf16 v[16:19], v[182:185], v[230:233], v[16:19]
	v_mfma_f32_16x16x32_bf16 v[28:31], v[190:193], v[230:233], v[28:31]
	v_mfma_f32_16x16x32_bf16 v[0:3], v[182:185], v[238:241], v[0:3]
	v_mfma_f32_16x16x32_bf16 v[12:15], v[190:193], v[238:241], v[12:15]
	v_mfma_f32_16x16x32_bf16 v[48:51], v[186:189], v[204:207], v[48:51]
	v_mfma_f32_16x16x32_bf16 v[60:63], v[194:197], v[204:207], v[60:63]
	v_mfma_f32_16x16x32_bf16 v[32:35], v[186:189], v[226:229], v[32:35]
	v_mfma_f32_16x16x32_bf16 v[44:47], v[194:197], v[226:229], v[44:47]
	v_mfma_f32_16x16x32_bf16 v[16:19], v[186:189], v[234:237], v[16:19]
	v_mfma_f32_16x16x32_bf16 v[28:31], v[194:197], v[234:237], v[28:31]
	v_mfma_f32_16x16x32_bf16 v[0:3], v[186:189], v[242:245], v[0:3]
	v_mfma_f32_16x16x32_bf16 v[12:15], v[194:197], v[242:245], v[12:15]
	s_barrier
	s_setprio 0
	s_add_i32 s99, s99, 2
	s_add_u32 s22, s22, 0x100
	s_addc_u32 s23, s23, 0
	s_add_u32 s93, s93, 0x100
	s_addc_u32 s98, s98, 0
	s_cmp_gt_u32 s99, 29
	s_cbranch_scc0 .LBB0_59
	s_and_b64 vcc, exec, s[84:85]
	s_cbranch_vccz .LBB0_62
	s_barrier

; #define LAS __attribute__((address_space(3)))
; __device__ __forceinline__ void attn_c_unit(LAS unsigned char* lds, const bf16_t* proj, const bf16_t* vt, bf16_t* obuf, int b, int hk, int blk, float mref, unsigned long long* sg) {
;     ...
;     const int pr = (r & ~12) | ((r & 4) << 1) | ((r & 8) >> 1);
;     constexpr int nT = SEQ / 64;
;     constexpr int CK = 0, CV = 4 * ATT_TILE;
; #pragma unroll
;     for (int i = 0; i < 2; ++i) { kreg = *(const u32x4*)(kg + (size_t)(i * 64) * INW); vreg = *(const u32x4*)(vg + i * 64);
;         *(LAS u32x4*)(lds + CK + i * ATT_TILE + sdst) = kreg; *(LAS u32x4*)(lds + CV + i * ATT_TILE + sdst) = vreg; }
;     __syncthreads();
;     for (int it = 0; it < nT; ++it) {
;         const int buf = it & 3;
;         if (it + 2 < nT) { kreg = *(const u32x4*)(kg + (size_t)((it + 2) * 64) * INW); vreg = *(const u32x4*)(vg + (it + 2) * 64); }
;         const LAS unsigned char* kb = lds + CK + buf * ATT_TILE + pr * KP + 16 * h;
;         f32x16 s00, s01, s10, s11;
;         {
;             const bf16x8 a0 = *(const LAS bf16x8*)(kb), a1 = *(const LAS bf16x8*)(kb + 32 * KP);
;             s00 = __builtin_amdgcn_mfma_f32_32x32x16_bf16(a0, qf[0][0], negm, 0, 0, 0);
;             s10 = __builtin_amdgcn_mfma_f32_32x32x16_bf16(a0, qf[1][0], negm, 0, 0, 0);
;             s01 = __builtin_amdgcn_mfma_f32_32x32x16_bf16(a1, qf[0][0], negm, 0, 0, 0);
;             s11 = __builtin_amdgcn_mfma_f32_32x32x16_bf16(a1, qf[1][0], negm, 0, 0, 0);
;         }
; #pragma unroll
;         for (int ks = 1; ks < 4; ++ks) {
;             const bf16x8 a0 = *(const LAS bf16x8*)(kb + 32 * ks), a1 = *(const LAS bf16x8*)(kb + 32 * KP + 32 * ks);
;             s00 = __builtin_amdgcn_mfma_f32_32x32x16_bf16(a0, qf[0][ks], s00, 0, 0, 0);
;             s10 = __builtin_amdgcn_mfma_f32_32x32x16_bf16(a0, qf[1][ks], s10, 0, 0, 0);
;             s01 = __builtin_amdgcn_mfma_f32_32x32x16_bf16(a1, qf[0][ks], s01, 0, 0, 0);
;             s11 = __builtin_amdgcn_mfma_f32_32x32x16_bf16(a1, qf[1][ks], s11, 0, 0, 0);
;         }
.LBB0_207:
	s_bfe_u32 s24, s11, 0x10002
	v_mov_b32_e32 v18, v199
	s_lshl_b32 s54, s24, 13
	v_ashrrev_i32_e32 v8, 3, v18
	v_add_u32_e32 v0, s54, v8
	v_mov_b64_e32 v[10:11], s[86:87]
	s_and_b32 s22, s11, 3
	s_waitcnt lgkmcnt(0)
	v_mad_i64_i32 v[0:1], s[12:13], v0, s25, v[10:11]
	s_mul_i32 s14, s24, 14
	s_lshl_b32 s12, s22, 7
	s_mov_b32 s13, s55
	v_lshlrev_b32_e32 v4, 4, v18
	s_add_i32 s15, s22, s14
	v_lshl_add_u64 v[0:1], v[0:1], 0, s[12:13]
	v_and_b32_e32 v128, 0x70, v4
	s_lshl_b32 s12, s15, 6
	v_lshl_add_u64 v[14:15], v[0:1], 0, v[128:129]
	v_ashrrev_i32_e32 v9, 31, v8
	s_addk_i32 s12, 0x280
	v_add_co_u32_e32 v0, vcc, s48, v14
	v_lshl_add_u64 v[2:3], s[12:13], 0, v[8:9]
	s_nop 0
	v_addc_co_u32_e32 v1, vcc, 0, v15, vcc
	s_mov_b32 s12, 0x79000
	v_add_co_u32_e32 v14, vcc, s12, v14
	s_and_b32 s12, s10, 3
	s_add_i32 s14, s14, s12
	s_lshl_b32 s13, s14, 6
	s_add_i32 s14, s13, 0x280
	s_lshl_b32 s26, s12, 7
	v_readfirstlane_b32 s12, v18
	s_lshl_b32 s13, s11, 4
	s_and_b32 s13, s13, 0xffffff80
	s_and_b32 s23, s12, 64
	v_and_b32_e32 v19, 31, v18
	s_or_b32 s13, s13, s23
	v_lshlrev_b64 v[2:3], 14, v[2:3]
	v_or_b32_e32 v182, s13, v19
	v_lshl_add_u64 v[2:3], s[84:85], 0, v[2:3]
	v_addc_co_u32_e32 v15, vcc, 0, v15, vcc
	s_ashr_i32 s12, s12, 1
	v_ashrrev_i32_e32 v183, 31, v182
	v_lshl_add_u64 v[12:13], v[2:3], 0, v[128:129]
	global_load_dwordx4 v[0:3], v[0:1], off offset:2560
	s_nop 0
	global_load_dwordx4 v[4:7], v[12:13], off
	global_load_dwordx4 v[130:133], v[14:15], off offset:2560
	global_load_dwordx4 v[134:137], v[12:13], off offset:128
	s_lshl_b32 s13, s22, 8
	s_andn2_b32 s12, s12, 63
	v_lshl_add_u64 v[184:185], v[182:183], 0, s[54:55]
	s_add_i32 s12, s12, s13
	v_mad_u64_u32 v[10:11], s[22:23], v184, s25, v[10:11]
	v_bfe_u32 v196, v18, 5, 1
	v_mad_i32_i24 v11, v185, s25, v11
	s_ashr_i32 s13, s12, 31
	v_lshl_add_u64 v[10:11], s[12:13], 1, v[10:11]
	v_lshlrev_b32_e32 v12, 4, v196
	v_mov_b32_e32 v13, v129
	v_lshl_add_u64 v[10:11], v[10:11], 0, v[12:13]
	s_mov_b64 s[22:23], 0x1200
	v_add_co_u32_e32 v16, vcc, s48, v10
	v_lshl_add_u64 v[14:15], v[10:11], 0, s[22:23]
	s_nop 0
	v_addc_co_u32_e32 v17, vcc, 0, v11, vcc
	s_mov_b32 s23, 0x3d000
	v_add_co_u32_e32 v10, vcc, s23, v10
	global_load_dwordx4 v[138:141], v[14:15], off offset:32
	global_load_dwordx4 v[142:145], v[14:15], off offset:64
	global_load_dwordx4 v[146:149], v[16:17], off offset:512
	global_load_dwordx4 v[150:153], v[14:15], off offset:96
	v_addc_co_u32_e32 v11, vcc, 0, v11, vcc
	global_load_dwordx4 v[154:157], v[10:11], off offset:512
	global_load_dwordx4 v[158:161], v[10:11], off offset:544
	global_load_dwordx4 v[162:165], v[10:11], off offset:576
	global_load_dwordx4 v[166:169], v[10:11], off offset:608
	v_mul_lo_u32 v10, v8, s16
	v_lshlrev_b32_e32 v11, 1, v18
	v_lshrrev_b32_e32 v13, 1, v18
	v_add3_u32 v197, v10, v128, 0
	v_and_b32_e32 v11, 8, v11
	v_and_b32_e32 v13, 4, v13
	s_mov_b32 s15, s55
	v_mov_b32_e32 v32, 0
	s_mov_b32 s22, 0
	v_mov_b32_e32 v33, v32
	v_mov_b32_e32 v34, v32
	v_mov_b32_e32 v35, v32
	v_mov_b32_e32 v36, v32
	v_mov_b32_e32 v37, v32
	v_mov_b32_e32 v38, v32
	s_waitcnt vmcnt(11)
	ds_write_b128 v197, v[0:3]
	s_waitcnt vmcnt(10)
	ds_write_b128 v197, v[4:7] offset:36864
	s_waitcnt vmcnt(9)
	ds_write_b128 v197, v[130:133] offset:9216
	s_waitcnt vmcnt(8)
	ds_write_b128 v197, v[134:137] offset:46080
	v_and_b32_e32 v0, 19, v18
	v_or3_b32 v0, v0, v11, v13
	v_mul_u32_u24_e32 v0, 0x90, v0
	v_add3_u32 v198, 0, v0, v12
	v_mul_u32_u24_e32 v0, 0x90, v19
	v_add3_u32 v200, 0, v0, v12
	v_lshl_add_u64 v[0:1], v[8:9], 0, s[14:15]
	v_lshlrev_b64 v[0:1], 14, v[0:1]
	v_or_b32_e32 v0, v0, v128
	v_lshl_add_u64 v[186:187], s[4:5], 0, v[0:1]
	v_mad_i64_i32 v[0:1], s[14:15], v8, s25, 0
	v_mad_u64_u32 v[0:1], s[14:15], s24, v222, v[0:1]
	v_or3_b32 v0, v0, s26, v128
	v_lshl_add_u64 v[188:189], s[6:7], 0, v[0:1]
	v_mov_b32_e32 v39, v32
	v_mov_b32_e32 v40, v32
	v_mov_b32_e32 v41, v32
	v_mov_b32_e32 v42, v32
	v_mov_b32_e32 v43, v32
	v_mov_b32_e32 v44, v32
	v_mov_b32_e32 v45, v32
	v_mov_b32_e32 v46, v32
	v_mov_b32_e32 v47, v32
	v_mov_b32_e32 v48, v32
	v_mov_b32_e32 v49, v32
	v_mov_b32_e32 v50, v32
	v_mov_b32_e32 v51, v32
	v_mov_b32_e32 v52, v32
	v_mov_b32_e32 v53, v32
	v_mov_b32_e32 v54, v32
	v_mov_b32_e32 v55, v32
	v_mov_b32_e32 v56, v32
	v_mov_b32_e32 v57, v32
	v_mov_b32_e32 v58, v32
	v_mov_b32_e32 v59, v32
	v_mov_b32_e32 v60, v32
	v_mov_b32_e32 v61, v32
	v_mov_b32_e32 v62, v32
	v_mov_b32_e32 v63, v32
	v_mov_b32_e32 v0, v32
	v_mov_b32_e32 v1, v32
	v_mov_b32_e32 v2, v32
	v_mov_b32_e32 v3, v32
	v_mov_b32_e32 v4, v32
	v_mov_b32_e32 v5, v32
	v_mov_b32_e32 v6, v32
	v_mov_b32_e32 v7, v32
	v_mov_b32_e32 v8, v32
	v_mov_b32_e32 v9, v32
	v_mov_b32_e32 v10, v32
	v_mov_b32_e32 v11, v32
	v_mov_b32_e32 v12, v32
	v_mov_b32_e32 v13, v32
	v_mov_b32_e32 v14, v32
	v_mov_b32_e32 v15, v32
	v_mov_b32_e32 v16, v32
	v_mov_b32_e32 v17, v32
	v_mov_b32_e32 v18, v32
	v_mov_b32_e32 v19, v32
	v_mov_b32_e32 v20, v32
	v_mov_b32_e32 v21, v32
	v_mov_b32_e32 v22, v32
	v_mov_b32_e32 v23, v32
	v_mov_b32_e32 v24, v32
	v_mov_b32_e32 v25, v32
	v_mov_b32_e32 v26, v32
	v_mov_b32_e32 v27, v32
	v_mov_b32_e32 v28, v32
	v_mov_b32_e32 v29, v32
	v_mov_b32_e32 v30, v32
	v_mov_b32_e32 v31, v32
	v_mov_b32_e32 v190, v32
	v_mov_b32_e32 v191, v32
	s_waitcnt vmcnt(0) lgkmcnt(0)
	s_barrier
	ds_read_b128 v[226:229], v198 offset:0
	ds_read_b128 v[230:233], v198 offset:32
	ds_read_b128 v[234:237], v198 offset:64
	ds_read_b128 v[238:241], v198 offset:96
	ds_read_b128 v[202:205], v200 offset:36928
	ds_read_b128 v[192:195], v200 offset:41536
	ds_read_b128 v[210:213], v200 offset:36960
	ds_read_b128 v[242:245], v200 offset:41568
	v_mov_b32_e32 v214, 0
	v_mov_b32_e32 v215, 0
	v_mov_b32_e32 v96, 0
	v_mov_b32_e32 v97, 0
	v_mov_b32_e32 v98, 0
	v_mov_b32_e32 v99, 0
	v_mov_b32_e32 v100, 0
	v_mov_b32_e32 v101, 0
	v_mov_b32_e32 v102, 0
	v_mov_b32_e32 v103, 0
	v_mov_b32_e32 v112, 0
	v_mov_b32_e32 v113, 0
	v_mov_b32_e32 v114, 0
	v_mov_b32_e32 v115, 0
	v_mov_b32_e32 v116, 0
	v_mov_b32_e32 v117, 0
	v_mov_b32_e32 v118, 0
	v_mov_b32_e32 v119, 0
	v_mov_b32_e32 v128, v198
	s_waitcnt lgkmcnt(4)
	v_mfma_f32_32x32x16_bf16 v[64:79], v[226:229], v[146:149], 0
	v_mfma_f32_32x32x16_bf16 v[80:95], v[226:229], v[154:157], 0
	ds_read_b128 v[226:229], v128 offset:4608
	v_mfma_f32_32x32x16_bf16 v[64:79], v[230:233], v[138:141], v[64:79]
	v_mfma_f32_32x32x16_bf16 v[80:95], v[230:233], v[158:161], v[80:95]
	ds_read_b128 v[230:233], v128 offset:4640
	v_mfma_f32_32x32x16_bf16 v[64:79], v[234:237], v[142:145], v[64:79]
	v_mfma_f32_32x32x16_bf16 v[80:95], v[234:237], v[162:165], v[80:95]
	ds_read_b128 v[234:237], v128 offset:4672
	v_mfma_f32_32x32x16_bf16 v[64:79], v[238:241], v[150:153], v[64:79]
	v_mfma_f32_32x32x16_bf16 v[80:95], v[238:241], v[166:169], v[80:95]
	ds_read_b128 v[238:241], v128 offset:4704
	s_nop 7
; __device__ __forceinline__ void attn_c_unit(LAS unsigned char* lds, const bf16_t* proj, const bf16_t* vt, bf16_t* obuf, int b, int hk, int blk, float mref, unsigned long long* sg) {
;     ...
;     for (int it = 0; it < nT; ++it) {
;         const int buf = it & 3;
;         if (it + 2 < nT) { kreg = *(const u32x4*)(kg + (size_t)((it + 2) * 64) * INW); vreg = *(const u32x4*)(vg + (it + 2) * 64); }
;         const LAS unsigned char* kb = lds + CK + buf * ATT_TILE + pr * KP + 16 * h;
;         f32x16 s00, s01, s10, s11;
;         {
;             const bf16x8 a0 = *(const LAS bf16x8*)(kb), a1 = *(const LAS bf16x8*)(kb + 32 * KP);
;             s00 = __builtin_amdgcn_mfma_f32_32x32x16_bf16(a0, qf[0][0], negm, 0, 0, 0);
;             s10 = __builtin_amdgcn_mfma_f32_32x32x16_bf16(a0, qf[1][0], negm, 0, 0, 0);
;             s01 = __builtin_amdgcn_mfma_f32_32x32x16_bf16(a1, qf[0][0], negm, 0, 0, 0);
;             s11 = __builtin_amdgcn_mfma_f32_32x32x16_bf16(a1, qf[1][0], negm, 0, 0, 0);
;         }
; #pragma unroll
;         for (int ks = 1; ks < 4; ++ks) {
;             const bf16x8 a0 = *(const LAS bf16x8*)(kb + 32 * ks), a1 = *(const LAS bf16x8*)(kb + 32 * KP + 32 * ks);
;             s00 = __builtin_amdgcn_mfma_f32_32x32x16_bf16(a0, qf[0][ks], s00, 0, 0, 0);
;             s10 = __builtin_amdgcn_mfma_f32_32x32x16_bf16(a0, qf[1][ks], s10, 0, 0, 0);
;             s01 = __builtin_amdgcn_mfma_f32_32x32x16_bf16(a1, qf[0][ks], s01, 0, 0, 0);
;             s11 = __builtin_amdgcn_mfma_f32_32x32x16_bf16(a1, qf[1][ks], s11, 0, 0, 0);
;         }
;         u32x4 pw0[4], pw1[4];
;         {
;             float ps = 0.f;
; #pragma unroll
;             for (int i = 0; i < 16; ++i) { s00[i] = __builtin_amdgcn_exp2f(s00[i]); s01[i] = __builtin_amdgcn_exp2f(s01[i]); ps += s00[i] + s01[i]; }
;             l0 += ps;
; #pragma unroll
;             for (int q = 0; q < 4; ++q) { pw0[0][q] = pk_bf16(s00[2 * q], s00[2 * q + 1]); pw0[1][q] = pk_bf16(s00[8 + 2 * q], s00[8 + 2 * q + 1]);
;                                           pw0[2][q] = pk_bf16(s01[2 * q], s01[2 * q + 1]); pw0[3][q] = pk_bf16(s01[8 + 2 * q], s01[8 + 2 * q + 1]); }
;         }
;         {
;             float ps = 0.f;
; #pragma unroll
;             for (int i = 0; i < 16; ++i) { s10[i] = __builtin_amdgcn_exp2f(s10[i]); s11[i] = __builtin_amdgcn_exp2f(s11[i]); ps += s10[i] + s11[i]; }
;             l1 += ps;
; #pragma unroll
.Lc_top:
	s_waitcnt lgkmcnt(4)
	v_mfma_f32_32x32x16_bf16 v[32:47], v[202:205], v[96:99], v[32:47]
	s_cmpk_gt_u32 s22, 0x7d
	s_cbranch_scc1 .Lc_noload
	global_load_dwordx4 v[130:133], v[188:189], off
	global_load_dwordx4 v[134:137], v[186:187], off
.Lc_noload:
	v_exp_f32_e32 v64, v64
	v_exp_f32_e32 v65, v65
	v_exp_f32_e32 v66, v66
	v_exp_f32_e32 v67, v67
	v_add_f32_e32 v190, v190, v64
	v_mfma_f32_32x32x16_bf16 v[0:15], v[202:205], v[112:115], v[0:15]
	s_and_b32 s24, s22, 7
	s_mulk_i32 s24, 0x2400
	v_add_f32_e32 v214, v214, v65
	v_cvt_pk_bf16_f32 v64, v64, v65
	v_exp_f32_e32 v68, v68
	v_exp_f32_e32 v69, v69
	v_add_f32_e32 v190, v190, v66
	v_mfma_f32_32x32x16_bf16 v[48:63], v[192:195], v[96:99], v[48:63]
	v_add_u32_e32 v246, s24, v200
	v_add_f32_e32 v214, v214, v67
	v_cvt_pk_bf16_f32 v65, v66, v67
	v_exp_f32_e32 v70, v70
	v_exp_f32_e32 v71, v71
	v_add_f32_e32 v190, v190, v68
	v_mfma_f32_32x32x16_bf16 v[16:31], v[192:195], v[112:115], v[16:31]
	v_lshl_add_u64 v[186:187], v[186:187], 0, s[64:65]
	v_add_f32_e32 v214, v214, v69
	v_cvt_pk_bf16_f32 v66, v68, v69
	v_exp_f32_e32 v72, v72
	v_exp_f32_e32 v73, v73
	v_add_f32_e32 v190, v190, v70
	v_mfma_f32_32x32x16_bf16 v[32:47], v[210:213], v[100:103], v[32:47]
	v_lshl_add_u64 v[188:189], v[188:189], 0, s[68:69]
	v_add_f32_e32 v214, v214, v71
	v_cvt_pk_bf16_f32 v67, v70, v71
	v_exp_f32_e32 v74, v74
	v_exp_f32_e32 v75, v75
	v_add_f32_e32 v190, v190, v72
	v_mfma_f32_32x32x16_bf16 v[0:15], v[210:213], v[116:119], v[0:15]
	s_and_b32 s23, s22, 3
	s_mulk_i32 s23, 0x2400
	s_xor_b32 s23, s23, 0x4800
	v_add_f32_e32 v214, v214, v73
	v_cvt_pk_bf16_f32 v68, v72, v73
	v_exp_f32_e32 v76, v76
	v_exp_f32_e32 v77, v77
	v_add_f32_e32 v190, v190, v74
	v_mfma_f32_32x32x16_bf16 v[48:63], v[242:245], v[100:103], v[48:63]
	v_add_u32_e32 v201, s23, v197
	s_add_i32 s23, s22, 2
	s_and_b32 s23, s23, 7
	s_mulk_i32 s23, 0x2400
	v_add_f32_e32 v214, v214, v75
	v_cvt_pk_bf16_f32 v69, v74, v75
	v_exp_f32_e32 v78, v78
	v_exp_f32_e32 v79, v79
	v_add_f32_e32 v190, v190, v76
	v_mfma_f32_32x32x16_bf16 v[16:31], v[242:245], v[116:119], v[16:31]
	ds_read_b128 v[202:205], v246 offset:36864
	ds_read_b128 v[192:195], v246 offset:41472
	ds_read_b128 v[210:213], v246 offset:36896
	ds_read_b128 v[242:245], v246 offset:41504
	s_waitcnt lgkmcnt(4)
	v_add_f32_e32 v214, v214, v77
	v_cvt_pk_bf16_f32 v70, v76, v77
	v_add_f32_e32 v190, v190, v78
	v_add_f32_e32 v214, v214, v79
	v_cvt_pk_bf16_f32 v71, v78, v79
	v_mfma_f32_32x32x16_bf16 v[96:111], v[226:229], v[146:149], 0
	v_add_u32_e32 v206, s23, v197
	v_exp_f32_e32 v80, v80
	v_exp_f32_e32 v81, v81
	v_exp_f32_e32 v82, v82
	v_exp_f32_e32 v83, v83
	v_add_f32_e32 v191, v191, v80
	v_mfma_f32_32x32x16_bf16 v[112:127], v[226:229], v[154:157], 0
	s_cmpk_gt_u32 s22, 0x7d
	s_cbranch_scc1 .Lc_nostore
	s_waitcnt vmcnt(0)
	ds_write_b128 v201, v[130:133]
	ds_write_b128 v206, v[134:137] offset:36864
.Lc_nostore:
	v_add_f32_e32 v215, v215, v81
	v_cvt_pk_bf16_f32 v80, v80, v81
	v_exp_f32_e32 v84, v84
	v_exp_f32_e32 v85, v85
	v_add_f32_e32 v191, v191, v82
	v_mfma_f32_32x32x16_bf16 v[96:111], v[230:233], v[138:141], v[96:111]
	v_add_f32_e32 v215, v215, v83
	v_cvt_pk_bf16_f32 v81, v82, v83
	v_exp_f32_e32 v86, v86
	v_exp_f32_e32 v87, v87
	v_add_f32_e32 v191, v191, v84
	v_mfma_f32_32x32x16_bf16 v[112:127], v[230:233], v[158:161], v[112:127]
	v_add_f32_e32 v215, v215, v85
	v_cvt_pk_bf16_f32 v82, v84, v85
	v_exp_f32_e32 v88, v88
	v_exp_f32_e32 v89, v89
	v_add_f32_e32 v191, v191, v86
	v_mfma_f32_32x32x16_bf16 v[96:111], v[234:237], v[142:145], v[96:111]
	s_add_i32 s23, s22, 1
	s_and_b32 s23, s23, 3
	s_mulk_i32 s23, 0x2400
	v_add_f32_e32 v215, v215, v87
	v_cvt_pk_bf16_f32 v83, v86, v87
	v_exp_f32_e32 v90, v90
	v_exp_f32_e32 v91, v91
	v_add_f32_e32 v191, v191, v88
	v_mfma_f32_32x32x16_bf16 v[112:127], v[234:237], v[162:165], v[112:127]
	v_add_u32_e32 v128, s23, v198
	v_add_f32_e32 v215, v215, v89
	v_cvt_pk_bf16_f32 v84, v88, v89
	v_exp_f32_e32 v92, v92
	v_exp_f32_e32 v93, v93
	v_add_f32_e32 v191, v191, v90
	v_mfma_f32_32x32x16_bf16 v[96:111], v[238:241], v[150:153], v[96:111]
	v_add_f32_e32 v215, v215, v91
	v_cvt_pk_bf16_f32 v85, v90, v91
	v_exp_f32_e32 v94, v94
	v_exp_f32_e32 v95, v95
	v_add_f32_e32 v191, v191, v92
	v_mfma_f32_32x32x16_bf16 v[112:127], v[238:241], v[166:169], v[112:127]
	v_add_f32_e32 v215, v215, v93
	v_cvt_pk_bf16_f32 v86, v92, v93
	v_add_f32_e32 v191, v191, v94
	v_add_f32_e32 v215, v215, v95
	v_cvt_pk_bf16_f32 v87, v94, v95
	s_bitcmp0_b32 s22, 0
	s_cbranch_scc1 .Lc_nobar
	s_waitcnt lgkmcnt(0)
	s_barrier
; __device__ __forceinline__ void attn_c_unit(LAS unsigned char* lds, const bf16_t* proj, const bf16_t* vt, bf16_t* obuf, int b, int hk, int blk, float mref, unsigned long long* sg) {
;     ...
;     for (int it = 0; it < nT; ++it) {
;         const int buf = it & 3;
;         if (it + 2 < nT) { kreg = *(const u32x4*)(kg + (size_t)((it + 2) * 64) * INW); vreg = *(const u32x4*)(vg + (it + 2) * 64); }
;         const LAS unsigned char* kb = lds + CK + buf * ATT_TILE + pr * KP + 16 * h;
;         f32x16 s00, s01, s10, s11;
;         {
;             const bf16x8 a0 = *(const LAS bf16x8*)(kb), a1 = *(const LAS bf16x8*)(kb + 32 * KP);
;             s00 = __builtin_amdgcn_mfma_f32_32x32x16_bf16(a0, qf[0][0], negm, 0, 0, 0);
;             s10 = __builtin_amdgcn_mfma_f32_32x32x16_bf16(a0, qf[1][0], negm, 0, 0, 0);
;             s01 = __builtin_amdgcn_mfma_f32_32x32x16_bf16(a1, qf[0][0], negm, 0, 0, 0);
;             s11 = __builtin_amdgcn_mfma_f32_32x32x16_bf16(a1, qf[1][0], negm, 0, 0, 0);
;         }
; #pragma unroll
;         for (int ks = 1; ks < 4; ++ks) {
;             const bf16x8 a0 = *(const LAS bf16x8*)(kb + 32 * ks), a1 = *(const LAS bf16x8*)(kb + 32 * KP + 32 * ks);
;             s00 = __builtin_amdgcn_mfma_f32_32x32x16_bf16(a0, qf[0][ks], s00, 0, 0, 0);
;             s10 = __builtin_amdgcn_mfma_f32_32x32x16_bf16(a0, qf[1][ks], s10, 0, 0, 0);
;             s01 = __builtin_amdgcn_mfma_f32_32x32x16_bf16(a1, qf[0][ks], s01, 0, 0, 0);
;             s11 = __builtin_amdgcn_mfma_f32_32x32x16_bf16(a1, qf[1][ks], s11, 0, 0, 0);
;         }
;         u32x4 pw0[4], pw1[4];
;         {
;             float ps = 0.f;
; #pragma unroll
;             for (int i = 0; i < 16; ++i) { s00[i] = __builtin_amdgcn_exp2f(s00[i]); s01[i] = __builtin_amdgcn_exp2f(s01[i]); ps += s00[i] + s01[i]; }
;             l0 += ps;
; #pragma unroll
;             for (int q = 0; q < 4; ++q) { pw0[0][q] = pk_bf16(s00[2 * q], s00[2 * q + 1]); pw0[1][q] = pk_bf16(s00[8 + 2 * q], s00[8 + 2 * q + 1]);
;                                           pw0[2][q] = pk_bf16(s01[2 * q], s01[2 * q + 1]); pw0[3][q] = pk_bf16(s01[8 + 2 * q], s01[8 + 2 * q + 1]); }
;         }
;         {
;             float ps = 0.f;
; #pragma unroll
;             for (int i = 0; i < 16; ++i) { s10[i] = __builtin_amdgcn_exp2f(s10[i]); s11[i] = __builtin_amdgcn_exp2f(s11[i]); ps += s10[i] + s11[i]; }
;             l1 += ps;
; #pragma unroll
.Lc_nobar:
	s_waitcnt lgkmcnt(0)
	v_mfma_f32_32x32x16_bf16 v[32:47], v[202:205], v[64:67], v[32:47]
	ds_read_b128 v[226:229], v128 offset:0
	ds_read_b128 v[230:233], v128 offset:32
	v_exp_f32_e32 v96, v96
	v_exp_f32_e32 v97, v97
	v_exp_f32_e32 v98, v98
	v_exp_f32_e32 v99, v99
	v_add_f32_e32 v190, v190, v96
	v_mfma_f32_32x32x16_bf16 v[0:15], v[202:205], v[80:83], v[0:15]
	ds_read_b128 v[234:237], v128 offset:64
	ds_read_b128 v[238:241], v128 offset:96
	v_add_f32_e32 v214, v214, v97
	v_cvt_pk_bf16_f32 v96, v96, v97
	v_exp_f32_e32 v100, v100
	v_exp_f32_e32 v101, v101
	v_add_f32_e32 v190, v190, v98
	v_mfma_f32_32x32x16_bf16 v[48:63], v[192:195], v[64:67], v[48:63]
	v_add_f32_e32 v214, v214, v99
	v_cvt_pk_bf16_f32 v97, v98, v99
	v_exp_f32_e32 v102, v102
	v_exp_f32_e32 v103, v103
	v_add_f32_e32 v190, v190, v100
	v_mfma_f32_32x32x16_bf16 v[16:31], v[192:195], v[80:83], v[16:31]
	v_add_f32_e32 v214, v214, v101
	v_cvt_pk_bf16_f32 v98, v100, v101
	v_exp_f32_e32 v104, v104
	v_exp_f32_e32 v105, v105
	v_add_f32_e32 v190, v190, v102
	v_mfma_f32_32x32x16_bf16 v[32:47], v[210:213], v[68:71], v[32:47]
	v_add_f32_e32 v214, v214, v103
	v_cvt_pk_bf16_f32 v99, v102, v103
	v_exp_f32_e32 v106, v106
	v_exp_f32_e32 v107, v107
	v_add_f32_e32 v190, v190, v104
	v_mfma_f32_32x32x16_bf16 v[0:15], v[210:213], v[84:87], v[0:15]
	v_add_f32_e32 v214, v214, v105
	v_cvt_pk_bf16_f32 v100, v104, v105
	v_exp_f32_e32 v108, v108
	v_exp_f32_e32 v109, v109
	v_add_f32_e32 v190, v190, v106
	v_mfma_f32_32x32x16_bf16 v[48:63], v[242:245], v[68:71], v[48:63]
	v_add_f32_e32 v214, v214, v107
	v_cvt_pk_bf16_f32 v101, v106, v107
	v_exp_f32_e32 v110, v110
	v_exp_f32_e32 v111, v111
	v_add_f32_e32 v190, v190, v108
	v_mfma_f32_32x32x16_bf16 v[16:31], v[242:245], v[84:87], v[16:31]
	ds_read_b128 v[202:205], v246 offset:36928
	ds_read_b128 v[192:195], v246 offset:41536
	ds_read_b128 v[210:213], v246 offset:36960
	ds_read_b128 v[242:245], v246 offset:41568
	s_waitcnt lgkmcnt(4)
	v_add_f32_e32 v214, v214, v109
	v_cvt_pk_bf16_f32 v102, v108, v109
	v_add_f32_e32 v190, v190, v110
	v_add_f32_e32 v214, v214, v111
	v_cvt_pk_bf16_f32 v103, v110, v111
	v_mfma_f32_32x32x16_bf16 v[64:79], v[226:229], v[146:149], 0
	v_exp_f32_e32 v112, v112
	v_exp_f32_e32 v113, v113
	v_exp_f32_e32 v114, v114
	v_exp_f32_e32 v115, v115
	v_add_f32_e32 v191, v191, v112
	v_mfma_f32_32x32x16_bf16 v[80:95], v[226:229], v[154:157], 0
	ds_read_b128 v[226:229], v128 offset:4608
	v_add_f32_e32 v215, v215, v113
	v_cvt_pk_bf16_f32 v112, v112, v113
	v_exp_f32_e32 v116, v116
	v_exp_f32_e32 v117, v117
	v_add_f32_e32 v191, v191, v114
	v_mfma_f32_32x32x16_bf16 v[64:79], v[230:233], v[138:141], v[64:79]
	v_add_f32_e32 v215, v215, v115
	v_cvt_pk_bf16_f32 v113, v114, v115
	v_exp_f32_e32 v118, v118
	v_exp_f32_e32 v119, v119
	v_add_f32_e32 v191, v191, v116
	v_mfma_f32_32x32x16_bf16 v[80:95], v[230:233], v[158:161], v[80:95]
	ds_read_b128 v[230:233], v128 offset:4640
	v_add_f32_e32 v215, v215, v117
	v_cvt_pk_bf16_f32 v114, v116, v117
	v_exp_f32_e32 v120, v120
	v_exp_f32_e32 v121, v121
	v_add_f32_e32 v191, v191, v118
	v_mfma_f32_32x32x16_bf16 v[64:79], v[234:237], v[142:145], v[64:79]
	s_add_i32 s22, s22, 1
	v_add_f32_e32 v215, v215, v119
	v_cvt_pk_bf16_f32 v115, v118, v119
	v_exp_f32_e32 v122, v122
	v_exp_f32_e32 v123, v123
	v_add_f32_e32 v191, v191, v120
	v_mfma_f32_32x32x16_bf16 v[80:95], v[234:237], v[162:165], v[80:95]
	ds_read_b128 v[234:237], v128 offset:4672
	v_add_f32_e32 v215, v215, v121
	v_cvt_pk_bf16_f32 v116, v120, v121
	v_exp_f32_e32 v124, v124
	v_exp_f32_e32 v125, v125
	v_add_f32_e32 v191, v191, v122
	v_mfma_f32_32x32x16_bf16 v[64:79], v[238:241], v[150:153], v[64:79]
	v_add_f32_e32 v215, v215, v123
	v_cvt_pk_bf16_f32 v117, v122, v123
	v_exp_f32_e32 v126, v126
	v_exp_f32_e32 v127, v127
	v_add_f32_e32 v191, v191, v124
	v_mfma_f32_32x32x16_bf16 v[80:95], v[238:241], v[166:169], v[80:95]
	ds_read_b128 v[238:241], v128 offset:4704
	v_add_f32_e32 v215, v215, v125
	v_cvt_pk_bf16_f32 v118, v124, v125
	v_add_f32_e32 v191, v191, v126
	v_add_f32_e32 v215, v215, v127
	v_cvt_pk_bf16_f32 v119, v126, v127
	s_cmpk_eq_i32 s22, 0x80
	s_cbranch_scc0 .Lc_top
	s_waitcnt lgkmcnt(0)
	v_mfma_f32_32x32x16_bf16 v[32:47], v[202:205], v[96:99], v[32:47]
	v_mfma_f32_32x32x16_bf16 v[0:15], v[202:205], v[112:115], v[0:15]
	v_mfma_f32_32x32x16_bf16 v[48:63], v[192:195], v[96:99], v[48:63]
	v_mfma_f32_32x32x16_bf16 v[16:31], v[192:195], v[112:115], v[16:31]
	v_mfma_f32_32x32x16_bf16 v[32:47], v[210:213], v[100:103], v[32:47]
	v_mfma_f32_32x32x16_bf16 v[0:15], v[210:213], v[116:119], v[0:15]
	v_mfma_f32_32x32x16_bf16 v[48:63], v[242:245], v[100:103], v[48:63]
	v_mfma_f32_32x32x16_bf16 v[16:31], v[242:245], v[116:119], v[16:31]
	v_add_f32_e32 v190, v190, v214
	v_add_f32_e32 v191, v191, v215
	s_barrier

; #define PG8_STAGE(bufoff, gbase, voff) do { _Pragma("unroll") for (int _i = 0; _i < 2; ++_i) \
;         __builtin_amdgcn_global_load_lds((const unsigned*)((const char*)(gbase) + (voff)[_i]), (PG8_LAS unsigned*)(lds + (bufoff) + ldsw + _i * 8192), 16, 0, 0); } while (0)
; #define PG8_LDA(dst, b, h) do { _Pragma("unroll") for (int m = 0; m < 4; ++m) _Pragma("unroll") for (int k = 0; k < 2; ++k) dst[m][k] = *(const PG8_LAS bf16x8*)(lds + PG8_SA(b, h) + aoff + m * 2048 + k * 1024); } while (0)
; #define PG8_LDB(dst, b, h) do { _Pragma("unroll") for (int n = 0; n < 2; ++n) _Pragma("unroll") for (int k = 0; k < 2; ++k) dst[n][k] = *(const PG8_LAS bf16x8*)(lds + PG8_SB(b, h) + boff + n * 2048 + k * 1024); } while (0)
; #define PG8_MMA(ai, bj, At, Bt) do { __builtin_amdgcn_s_setprio(1); _Pragma("unroll") for (int m = 0; m < 4; ++m) _Pragma("unroll") for (int n = 0; n < 2; ++n) _Pragma("unroll") for (int k = 0; k < 2; ++k) \
;         acc[ai][bj][m][n] = __builtin_amdgcn_mfma_f32_16x16x32_bf16(Bt[n][k], At[m][k], acc[ai][bj][m][n], 0, 0, 0); __builtin_amdgcn_s_setprio(0); } while (0)
; #define PG8_WAIT_V(n) asm volatile("s_waitcnt vmcnt(" #n ")" ::: "memory")
; #define PG8_WAIT_L(n) asm volatile("s_waitcnt lgkmcnt(" #n ")" ::: "memory")
; template <class Epi, class Sched, bool ALIGN_EPI = false, bool SP2 = false, class Hook = NoHook, bool REVK = false>
; __device__ __forceinline__ void gemm_phase(PG8_LAS unsigned char* lds, const Gemm g, const Sched& S, const Epi& E, const Hook H = Hook()) {
;     ...
;             const char* a1 = cA + (long)(t + 1) * kstep;
;             const char* a2 = last ? nA : cA + (long)(t + 2) * kstep; const char* b2 = last ? nB : cB + (long)(t + 2) * kstep;
;             const char* a3 = a2 + kstep; const char* b3 = b2 + kstep;
;             if (last && has_next) S.a_ready(nxt);
;             if constexpr (SP2) {
;             PG8_LDB(B0, 0, 0); PG8_LDB(B1, 0, 1); PG8_SCHED; PG8_LDA(At, 0, 0); PG8_STAGE(PG8_SA(1, 1), a1 + hstep, voffA);
;             PG8_WAIT_V(8); PG8_WAIT_L(0); PG8_BAR; PG8_MMA(0, 0, At, B0); PG8_MMA(0, 1, At, B1); PG8_BAR; PG8_SCHED;
;             PG8_LDA(At, 0, 1); PG8_STAGE(PG8_SB(0, 0), b2, voffB); PG8_STAGE(PG8_SB(0, 1), b2 + hstep, voffB); PG8_STAGE(PG8_SA(0, 0), a2, voffA);
;             PG8_WAIT_V(8); PG8_WAIT_L(0); PG8_BAR; PG8_MMA(1, 0, At, B0); PG8_MMA(1, 1, At, B1); PG8_BAR; PG8_SCHED;
.LBB0_477:
	s_add_u32 s20, s22, 0xfff80080
	s_addc_u32 s21, s23, -1
	s_add_i32 s46, 0, 0x10000
	s_cmp_eq_u32 s53, 30
	s_cselect_b32 s27, s11, s21
	s_cselect_b32 s26, s42, s20
	v_add_u32_e32 v128, s46, v226
	s_cselect_b32 s21, s43, s51
	s_cselect_b32 s20, s44, s47
	s_add_i32 s58, 0, 0x14000
	ds_read_b128 v[130:133], v128
	ds_read_b128 v[134:137], v128 offset:1024
	ds_read_b128 v[138:141], v128 offset:2048
	ds_read_b128 v[142:145], v128 offset:3072
	v_add_u32_e32 v128, s58, v226
	ds_read_b128 v[146:149], v128
	ds_read_b128 v[150:153], v128 offset:1024
	ds_read_b128 v[154:157], v128 offset:2048
	ds_read_b128 v[158:161], v128 offset:3072
	v_lshl_add_u64 v[196:197], s[22:23], 0, v[182:183]
	s_add_i32 m0, s34, 0xc000
	ds_read_b128 v[186:189], v229
	ds_read_b128 v[192:195], v229 offset:1024
	ds_read_b128 v[200:203], v229 offset:2048
	ds_read_b128 v[204:207], v229 offset:3072
	ds_read_b128 v[210:213], v229 offset:4096
	ds_read_b128 v[230:233], v229 offset:5120
	ds_read_b128 v[234:237], v229 offset:6144
	ds_read_b128 v[238:241], v229 offset:7168
	global_load_lds_dwordx4 v[196:197], off
	v_lshl_add_u64 v[196:197], s[22:23], 0, v[184:185]
	s_add_i32 m0, s34, 0xe000
	s_nop 0
	global_load_lds_dwordx4 v[196:197], off
	s_waitcnt vmcnt(8)
	s_waitcnt lgkmcnt(0)
	s_setprio 1
	s_barrier
	v_mfma_f32_16x16x32_bf16 v[124:127], v[130:133], v[186:189], v[124:127]
	v_mfma_f32_16x16x32_bf16 v[120:123], v[138:141], v[186:189], v[120:123]
	v_mfma_f32_16x16x32_bf16 v[108:111], v[130:133], v[200:203], v[108:111]
	v_mfma_f32_16x16x32_bf16 v[104:107], v[138:141], v[200:203], v[104:107]
	v_mfma_f32_16x16x32_bf16 v[92:95], v[130:133], v[210:213], v[92:95]
	v_mfma_f32_16x16x32_bf16 v[88:91], v[138:141], v[210:213], v[88:91]
	v_mfma_f32_16x16x32_bf16 v[76:79], v[130:133], v[234:237], v[76:79]
	v_mfma_f32_16x16x32_bf16 v[72:75], v[138:141], v[234:237], v[72:75]
	v_mfma_f32_16x16x32_bf16 v[124:127], v[134:137], v[192:195], v[124:127]
	v_mfma_f32_16x16x32_bf16 v[120:123], v[142:145], v[192:195], v[120:123]
	v_mfma_f32_16x16x32_bf16 v[108:111], v[134:137], v[204:207], v[108:111]
	v_mfma_f32_16x16x32_bf16 v[104:107], v[142:145], v[204:207], v[104:107]
	v_mfma_f32_16x16x32_bf16 v[92:95], v[134:137], v[230:233], v[92:95]
	v_mfma_f32_16x16x32_bf16 v[88:91], v[142:145], v[230:233], v[88:91]
	v_mfma_f32_16x16x32_bf16 v[76:79], v[134:137], v[238:241], v[76:79]
	v_mfma_f32_16x16x32_bf16 v[72:75], v[142:145], v[238:241], v[72:75]
	s_setprio 0
	s_setprio 1
	v_mfma_f32_16x16x32_bf16 v[116:119], v[146:149], v[186:189], v[116:119]
	v_mfma_f32_16x16x32_bf16 v[112:115], v[154:157], v[186:189], v[112:115]
	v_mfma_f32_16x16x32_bf16 v[100:103], v[146:149], v[200:203], v[100:103]
	v_mfma_f32_16x16x32_bf16 v[96:99], v[154:157], v[200:203], v[96:99]
	v_mfma_f32_16x16x32_bf16 v[84:87], v[146:149], v[210:213], v[84:87]
	v_mfma_f32_16x16x32_bf16 v[80:83], v[154:157], v[210:213], v[80:83]
	v_mfma_f32_16x16x32_bf16 v[68:71], v[146:149], v[234:237], v[68:71]
	v_mfma_f32_16x16x32_bf16 v[64:67], v[154:157], v[234:237], v[64:67]
	v_mfma_f32_16x16x32_bf16 v[116:119], v[150:153], v[192:195], v[116:119]
	v_mfma_f32_16x16x32_bf16 v[112:115], v[158:161], v[192:195], v[112:115]
	v_mfma_f32_16x16x32_bf16 v[100:103], v[150:153], v[204:207], v[100:103]
	v_mfma_f32_16x16x32_bf16 v[96:99], v[158:161], v[204:207], v[96:99]
	v_mfma_f32_16x16x32_bf16 v[84:87], v[150:153], v[230:233], v[84:87]
	v_mfma_f32_16x16x32_bf16 v[80:83], v[158:161], v[230:233], v[80:83]
	v_mfma_f32_16x16x32_bf16 v[68:71], v[150:153], v[238:241], v[68:71]
	v_mfma_f32_16x16x32_bf16 v[64:67], v[158:161], v[238:241], v[64:67]
	s_barrier
	s_setprio 0
	s_add_i32 s46, s46, s24
	v_lshl_add_u64 v[196:197], s[20:21], 0, v[166:167]
	s_mov_b32 m0, s46
	ds_read_b128 v[186:189], v229 offset:16384
	ds_read_b128 v[192:195], v229 offset:17408
	ds_read_b128 v[200:203], v229 offset:18432
	ds_read_b128 v[204:207], v229 offset:19456
	ds_read_b128 v[210:213], v229 offset:20480
	ds_read_b128 v[230:233], v229 offset:21504
	ds_read_b128 v[234:237], v229 offset:22528
	ds_read_b128 v[238:241], v229 offset:23552
	global_load_lds_dwordx4 v[196:197], off
	s_add_i32 m0, s46, 0x2000
	s_add_u32 s56, s20, 0x80000
	v_lshl_add_u64 v[214:215], s[20:21], 0, v[162:163]
	s_addc_u32 s57, s21, 0
	s_add_i32 s46, s58, s24
	global_load_lds_dwordx4 v[214:215], off
	v_lshl_add_u64 v[242:243], s[56:57], 0, v[166:167]
	s_mov_b32 m0, s46
	v_lshl_add_u64 v[244:245], s[26:27], 0, v[164:165]
	global_load_lds_dwordx4 v[242:243], off
	v_lshl_add_u64 v[242:243], s[56:57], 0, v[162:163]
	s_add_i32 m0, s46, 0x2000
	s_nop 0
	global_load_lds_dwordx4 v[242:243], off
	v_lshl_add_u64 v[242:243], s[26:27], 0, v[168:169]
	s_mov_b32 m0, s34
	s_nop 0
	global_load_lds_dwordx4 v[242:243], off
	s_mov_b32 m0, s35
	s_nop 0
	global_load_lds_dwordx4 v[244:245], off
	s_waitcnt vmcnt(8)
	s_waitcnt lgkmcnt(0)
	s_setprio 1
	s_barrier
; #define PG8_STAGE(bufoff, gbase, voff) do { _Pragma("unroll") for (int _i = 0; _i < 2; ++_i) \
;         __builtin_amdgcn_global_load_lds((const unsigned*)((const char*)(gbase) + (voff)[_i]), (PG8_LAS unsigned*)(lds + (bufoff) + ldsw + _i * 8192), 16, 0, 0); } while (0)
; #define PG8_LDA(dst, b, h) do { _Pragma("unroll") for (int m = 0; m < 4; ++m) _Pragma("unroll") for (int k = 0; k < 2; ++k) dst[m][k] = *(const PG8_LAS bf16x8*)(lds + PG8_SA(b, h) + aoff + m * 2048 + k * 1024); } while (0)
; #define PG8_LDB(dst, b, h) do { _Pragma("unroll") for (int n = 0; n < 2; ++n) _Pragma("unroll") for (int k = 0; k < 2; ++k) dst[n][k] = *(const PG8_LAS bf16x8*)(lds + PG8_SB(b, h) + boff + n * 2048 + k * 1024); } while (0)
; #define PG8_MMA(ai, bj, At, Bt) do { __builtin_amdgcn_s_setprio(1); _Pragma("unroll") for (int m = 0; m < 4; ++m) _Pragma("unroll") for (int n = 0; n < 2; ++n) _Pragma("unroll") for (int k = 0; k < 2; ++k) \
;         acc[ai][bj][m][n] = __builtin_amdgcn_mfma_f32_16x16x32_bf16(Bt[n][k], At[m][k], acc[ai][bj][m][n], 0, 0, 0); __builtin_amdgcn_s_setprio(0); } while (0)
; #define PG8_WAIT_V(n) asm volatile("s_waitcnt vmcnt(" #n ")" ::: "memory")
; #define PG8_WAIT_L(n) asm volatile("s_waitcnt lgkmcnt(" #n ")" ::: "memory")
; #define PG8_BAR __builtin_amdgcn_s_barrier()
; #define PG8_SCHED __builtin_amdgcn_sched_barrier(0)
; template <class Epi, class Sched, bool ALIGN_EPI = false, bool SP2 = false, class Hook = NoHook, bool REVK = false>
; __device__ __forceinline__ void gemm_phase(PG8_LAS unsigned char* lds, const Gemm g, const Sched& S, const Epi& E, const Hook H = Hook()) {
;     ...
;             PG8_WAIT_V(8); PG8_WAIT_L(0); PG8_BAR; PG8_MMA(1, 0, At, B0); PG8_MMA(1, 1, At, B1); PG8_BAR; PG8_SCHED;
;             PG8_LDB(B0, 1, 0); PG8_LDB(B1, 1, 1); PG8_SCHED; PG8_LDA(At, 1, 0); PG8_STAGE(PG8_SA(0, 1), a2 + hstep, voffA);
;             PG8_WAIT_V(8); PG8_WAIT_L(0); PG8_BAR; PG8_MMA(0, 0, At, B0); PG8_MMA(0, 1, At, B1); PG8_BAR; PG8_SCHED;
	v_mfma_f32_16x16x32_bf16 v[60:63], v[130:133], v[186:189], v[60:63]
	v_mfma_f32_16x16x32_bf16 v[56:59], v[138:141], v[186:189], v[56:59]
	v_mfma_f32_16x16x32_bf16 v[44:47], v[130:133], v[200:203], v[44:47]
	v_mfma_f32_16x16x32_bf16 v[40:43], v[138:141], v[200:203], v[40:43]
	v_mfma_f32_16x16x32_bf16 v[28:31], v[130:133], v[210:213], v[28:31]
	v_mfma_f32_16x16x32_bf16 v[24:27], v[138:141], v[210:213], v[24:27]
	v_mfma_f32_16x16x32_bf16 v[12:15], v[130:133], v[234:237], v[12:15]
	v_mfma_f32_16x16x32_bf16 v[8:11], v[138:141], v[234:237], v[8:11]
	v_mfma_f32_16x16x32_bf16 v[60:63], v[134:137], v[192:195], v[60:63]
	v_mfma_f32_16x16x32_bf16 v[56:59], v[142:145], v[192:195], v[56:59]
	v_mfma_f32_16x16x32_bf16 v[44:47], v[134:137], v[204:207], v[44:47]
	v_mfma_f32_16x16x32_bf16 v[40:43], v[142:145], v[204:207], v[40:43]
	v_mfma_f32_16x16x32_bf16 v[28:31], v[134:137], v[230:233], v[28:31]
	v_mfma_f32_16x16x32_bf16 v[24:27], v[142:145], v[230:233], v[24:27]
	v_mfma_f32_16x16x32_bf16 v[12:15], v[134:137], v[238:241], v[12:15]
	v_mfma_f32_16x16x32_bf16 v[8:11], v[142:145], v[238:241], v[8:11]
	s_setprio 0
	s_setprio 1
	v_mfma_f32_16x16x32_bf16 v[52:55], v[146:149], v[186:189], v[52:55]
	v_mfma_f32_16x16x32_bf16 v[48:51], v[154:157], v[186:189], v[48:51]
	v_mfma_f32_16x16x32_bf16 v[36:39], v[146:149], v[200:203], v[36:39]
	v_mfma_f32_16x16x32_bf16 v[32:35], v[154:157], v[200:203], v[32:35]
	v_mfma_f32_16x16x32_bf16 v[20:23], v[146:149], v[210:213], v[20:23]
	v_mfma_f32_16x16x32_bf16 v[16:19], v[154:157], v[210:213], v[16:19]
	v_mfma_f32_16x16x32_bf16 v[4:7], v[146:149], v[234:237], v[4:7]
	v_mfma_f32_16x16x32_bf16 v[0:3], v[154:157], v[234:237], v[0:3]
	v_mfma_f32_16x16x32_bf16 v[52:55], v[150:153], v[192:195], v[52:55]
	v_mfma_f32_16x16x32_bf16 v[48:51], v[158:161], v[192:195], v[48:51]
	v_mfma_f32_16x16x32_bf16 v[36:39], v[150:153], v[204:207], v[36:39]
	v_mfma_f32_16x16x32_bf16 v[32:35], v[158:161], v[204:207], v[32:35]
	v_mfma_f32_16x16x32_bf16 v[20:23], v[150:153], v[230:233], v[20:23]
	v_mfma_f32_16x16x32_bf16 v[16:19], v[158:161], v[230:233], v[16:19]
	v_mfma_f32_16x16x32_bf16 v[4:7], v[150:153], v[238:241], v[4:7]
	v_mfma_f32_16x16x32_bf16 v[0:3], v[158:161], v[238:241], v[0:3]
	s_barrier
	s_setprio 0
	s_add_i32 s46, 0, 0x18000
	v_add_u32_e32 v128, s46, v226
	s_add_i32 s56, 0, 0x1c000
	ds_read_b128 v[130:133], v128
	ds_read_b128 v[134:137], v128 offset:1024
	ds_read_b128 v[138:141], v128 offset:2048
	ds_read_b128 v[142:145], v128 offset:3072
	v_add_u32_e32 v128, s56, v226
	ds_read_b128 v[146:149], v128
	ds_read_b128 v[150:153], v128 offset:1024
	ds_read_b128 v[154:157], v128 offset:2048
	ds_read_b128 v[158:161], v128 offset:3072
	s_add_u32 s26, s26, 0x80000
	s_addc_u32 s27, s27, 0
	s_mov_b32 m0, s36
	v_lshl_add_u64 v[246:247], s[26:27], 0, v[168:169]
	ds_read_b128 v[186:189], v229 offset:32768
	ds_read_b128 v[192:195], v229 offset:33792
	ds_read_b128 v[200:203], v229 offset:34816
	ds_read_b128 v[204:207], v229 offset:35840
	ds_read_b128 v[210:213], v229 offset:36864
	ds_read_b128 v[230:233], v229 offset:37888
	ds_read_b128 v[234:237], v229 offset:38912
	ds_read_b128 v[238:241], v229 offset:39936
	global_load_lds_dwordx4 v[246:247], off
	v_lshl_add_u64 v[246:247], s[26:27], 0, v[164:165]
	s_mov_b32 m0, s38
	s_nop 0
	global_load_lds_dwordx4 v[246:247], off
	s_waitcnt vmcnt(8)
	s_waitcnt lgkmcnt(0)
	s_setprio 1
	s_barrier
	v_mfma_f32_16x16x32_bf16 v[124:127], v[130:133], v[186:189], v[124:127]
	v_mfma_f32_16x16x32_bf16 v[120:123], v[138:141], v[186:189], v[120:123]
	v_mfma_f32_16x16x32_bf16 v[108:111], v[130:133], v[200:203], v[108:111]
	v_mfma_f32_16x16x32_bf16 v[104:107], v[138:141], v[200:203], v[104:107]
	v_mfma_f32_16x16x32_bf16 v[92:95], v[130:133], v[210:213], v[92:95]
	v_mfma_f32_16x16x32_bf16 v[88:91], v[138:141], v[210:213], v[88:91]
	v_mfma_f32_16x16x32_bf16 v[76:79], v[130:133], v[234:237], v[76:79]
	v_mfma_f32_16x16x32_bf16 v[72:75], v[138:141], v[234:237], v[72:75]
	v_mfma_f32_16x16x32_bf16 v[124:127], v[134:137], v[192:195], v[124:127]
	v_mfma_f32_16x16x32_bf16 v[120:123], v[142:145], v[192:195], v[120:123]
	v_mfma_f32_16x16x32_bf16 v[108:111], v[134:137], v[204:207], v[108:111]
	v_mfma_f32_16x16x32_bf16 v[104:107], v[142:145], v[204:207], v[104:107]
	v_mfma_f32_16x16x32_bf16 v[92:95], v[134:137], v[230:233], v[92:95]
	v_mfma_f32_16x16x32_bf16 v[88:91], v[142:145], v[230:233], v[88:91]
	v_mfma_f32_16x16x32_bf16 v[76:79], v[134:137], v[238:241], v[76:79]
	v_mfma_f32_16x16x32_bf16 v[72:75], v[142:145], v[238:241], v[72:75]
	s_setprio 0
	s_setprio 1
	v_mfma_f32_16x16x32_bf16 v[116:119], v[146:149], v[186:189], v[116:119]
	v_mfma_f32_16x16x32_bf16 v[112:115], v[154:157], v[186:189], v[112:115]
	v_mfma_f32_16x16x32_bf16 v[100:103], v[146:149], v[200:203], v[100:103]
	v_mfma_f32_16x16x32_bf16 v[96:99], v[154:157], v[200:203], v[96:99]
	v_mfma_f32_16x16x32_bf16 v[84:87], v[146:149], v[210:213], v[84:87]
	v_mfma_f32_16x16x32_bf16 v[80:83], v[154:157], v[210:213], v[80:83]
	v_mfma_f32_16x16x32_bf16 v[68:71], v[146:149], v[234:237], v[68:71]
	v_mfma_f32_16x16x32_bf16 v[64:67], v[154:157], v[234:237], v[64:67]
	v_mfma_f32_16x16x32_bf16 v[116:119], v[150:153], v[192:195], v[116:119]
	v_mfma_f32_16x16x32_bf16 v[112:115], v[158:161], v[192:195], v[112:115]
	v_mfma_f32_16x16x32_bf16 v[100:103], v[150:153], v[204:207], v[100:103]
	v_mfma_f32_16x16x32_bf16 v[96:99], v[158:161], v[204:207], v[96:99]
	v_mfma_f32_16x16x32_bf16 v[84:87], v[150:153], v[230:233], v[84:87]
	v_mfma_f32_16x16x32_bf16 v[80:83], v[158:161], v[230:233], v[80:83]
	v_mfma_f32_16x16x32_bf16 v[68:71], v[150:153], v[238:241], v[68:71]
	v_mfma_f32_16x16x32_bf16 v[64:67], v[158:161], v[238:241], v[64:67]
	s_barrier
; #define PG8_STAGE(bufoff, gbase, voff) do { _Pragma("unroll") for (int _i = 0; _i < 2; ++_i) \
;         __builtin_amdgcn_global_load_lds((const unsigned*)((const char*)(gbase) + (voff)[_i]), (PG8_LAS unsigned*)(lds + (bufoff) + ldsw + _i * 8192), 16, 0, 0); } while (0)
; #define PG8_LDA(dst, b, h) do { _Pragma("unroll") for (int m = 0; m < 4; ++m) _Pragma("unroll") for (int k = 0; k < 2; ++k) dst[m][k] = *(const PG8_LAS bf16x8*)(lds + PG8_SA(b, h) + aoff + m * 2048 + k * 1024); } while (0)
; #define PG8_MMA(ai, bj, At, Bt) do { __builtin_amdgcn_s_setprio(1); _Pragma("unroll") for (int m = 0; m < 4; ++m) _Pragma("unroll") for (int n = 0; n < 2; ++n) _Pragma("unroll") for (int k = 0; k < 2; ++k) \
;         acc[ai][bj][m][n] = __builtin_amdgcn_mfma_f32_16x16x32_bf16(Bt[n][k], At[m][k], acc[ai][bj][m][n], 0, 0, 0); __builtin_amdgcn_s_setprio(0); } while (0)
; #define PG8_WAIT_V(n) asm volatile("s_waitcnt vmcnt(" #n ")" ::: "memory")
; #define PG8_WAIT_L(n) asm volatile("s_waitcnt lgkmcnt(" #n ")" ::: "memory")
; #define PG8_BAR __builtin_amdgcn_s_barrier()
; #define PG8_SCHED __builtin_amdgcn_sched_barrier(0)
; template <class Epi, class Sched, bool ALIGN_EPI = false, bool SP2 = false, class Hook = NoHook, bool REVK = false>
; __device__ __forceinline__ void gemm_phase(PG8_LAS unsigned char* lds, const Gemm g, const Sched& S, const Epi& E, const Hook H = Hook()) {
;     ...
;             PG8_WAIT_V(8); PG8_WAIT_L(0); PG8_BAR; PG8_MMA(0, 0, At, B0); PG8_MMA(0, 1, At, B1); PG8_BAR; PG8_SCHED;
;             PG8_LDA(At, 1, 1); PG8_STAGE(PG8_SB(1, 0), b3, voffB); PG8_STAGE(PG8_SB(1, 1), b3 + hstep, voffB); PG8_STAGE(PG8_SA(1, 0), a3, voffA);
;             PG8_WAIT_V(8); PG8_WAIT_L(0); PG8_BAR; PG8_MMA(1, 0, At, B0); PG8_MMA(1, 1, At, B1); PG8_BAR; PG8_SCHED;
	s_setprio 0
	s_add_i32 s26, s46, s24
	v_lshl_add_u64 v[196:197], v[196:197], 0, s[64:65]
	s_mov_b32 m0, s26
	ds_read_b128 v[186:189], v229 offset:49152
	ds_read_b128 v[192:195], v229 offset:50176
	ds_read_b128 v[200:203], v229 offset:51200
	ds_read_b128 v[204:207], v229 offset:52224
	ds_read_b128 v[210:213], v229 offset:53248
	ds_read_b128 v[230:233], v229 offset:54272
	ds_read_b128 v[234:237], v229 offset:55296
	ds_read_b128 v[238:241], v229 offset:56320
	global_load_lds_dwordx4 v[196:197], off
	s_add_i32 m0, s26, 0x2000
	s_add_u32 s20, s20, 0x80080
	v_lshl_add_u64 v[196:197], v[214:215], 0, s[64:65]
	s_addc_u32 s21, s21, 0
	s_add_i32 s26, s56, s24
	global_load_lds_dwordx4 v[196:197], off
	v_lshl_add_u64 v[196:197], s[20:21], 0, v[166:167]
	s_mov_b32 m0, s26
	s_nop 0
	global_load_lds_dwordx4 v[196:197], off
	v_lshl_add_u64 v[196:197], s[20:21], 0, v[162:163]
	s_add_i32 m0, s26, 0x2000
	s_nop 0
	global_load_lds_dwordx4 v[196:197], off
	v_lshl_add_u64 v[196:197], v[242:243], 0, s[64:65]
	s_mov_b32 m0, s39
	s_nop 0
	global_load_lds_dwordx4 v[196:197], off
	v_lshl_add_u64 v[196:197], v[244:245], 0, s[64:65]
	s_mov_b32 m0, s40
	s_nop 0
	global_load_lds_dwordx4 v[196:197], off
	s_waitcnt vmcnt(8)
	s_waitcnt lgkmcnt(0)
	s_setprio 1
	s_barrier
	v_mfma_f32_16x16x32_bf16 v[60:63], v[130:133], v[186:189], v[60:63]
	v_mfma_f32_16x16x32_bf16 v[56:59], v[138:141], v[186:189], v[56:59]
	v_mfma_f32_16x16x32_bf16 v[44:47], v[130:133], v[200:203], v[44:47]
	v_mfma_f32_16x16x32_bf16 v[40:43], v[138:141], v[200:203], v[40:43]
	v_mfma_f32_16x16x32_bf16 v[28:31], v[130:133], v[210:213], v[28:31]
	v_mfma_f32_16x16x32_bf16 v[24:27], v[138:141], v[210:213], v[24:27]
	v_mfma_f32_16x16x32_bf16 v[12:15], v[130:133], v[234:237], v[12:15]
	v_mfma_f32_16x16x32_bf16 v[8:11], v[138:141], v[234:237], v[8:11]
	v_mfma_f32_16x16x32_bf16 v[60:63], v[134:137], v[192:195], v[60:63]
	v_mfma_f32_16x16x32_bf16 v[56:59], v[142:145], v[192:195], v[56:59]
	v_mfma_f32_16x16x32_bf16 v[44:47], v[134:137], v[204:207], v[44:47]
	v_mfma_f32_16x16x32_bf16 v[40:43], v[142:145], v[204:207], v[40:43]
	v_mfma_f32_16x16x32_bf16 v[28:31], v[134:137], v[230:233], v[28:31]
	v_mfma_f32_16x16x32_bf16 v[24:27], v[142:145], v[230:233], v[24:27]
	v_mfma_f32_16x16x32_bf16 v[12:15], v[134:137], v[238:241], v[12:15]
	v_mfma_f32_16x16x32_bf16 v[8:11], v[142:145], v[238:241], v[8:11]
	s_setprio 0
	s_setprio 1
	v_mfma_f32_16x16x32_bf16 v[52:55], v[146:149], v[186:189], v[52:55]
	v_mfma_f32_16x16x32_bf16 v[48:51], v[154:157], v[186:189], v[48:51]
	v_mfma_f32_16x16x32_bf16 v[36:39], v[146:149], v[200:203], v[36:39]
	v_mfma_f32_16x16x32_bf16 v[32:35], v[154:157], v[200:203], v[32:35]
	v_mfma_f32_16x16x32_bf16 v[20:23], v[146:149], v[210:213], v[20:23]
	v_mfma_f32_16x16x32_bf16 v[16:19], v[154:157], v[210:213], v[16:19]
	v_mfma_f32_16x16x32_bf16 v[4:7], v[146:149], v[234:237], v[4:7]
	v_mfma_f32_16x16x32_bf16 v[0:3], v[154:157], v[234:237], v[0:3]
	v_mfma_f32_16x16x32_bf16 v[52:55], v[150:153], v[192:195], v[52:55]
	v_mfma_f32_16x16x32_bf16 v[48:51], v[158:161], v[192:195], v[48:51]
	v_mfma_f32_16x16x32_bf16 v[36:39], v[150:153], v[204:207], v[36:39]
	v_mfma_f32_16x16x32_bf16 v[32:35], v[158:161], v[204:207], v[32:35]
	v_mfma_f32_16x16x32_bf16 v[20:23], v[150:153], v[230:233], v[20:23]
	v_mfma_f32_16x16x32_bf16 v[16:19], v[158:161], v[230:233], v[16:19]
	v_mfma_f32_16x16x32_bf16 v[4:7], v[150:153], v[238:241], v[4:7]
	v_mfma_f32_16x16x32_bf16 v[0:3], v[158:161], v[238:241], v[0:3]
	s_barrier
	s_setprio 0
	s_add_i32 s20, s53, 2
	s_add_u32 s22, s22, 0x100
	s_addc_u32 s23, s23, 0
	s_add_u32 s47, s47, 0x100
	s_addc_u32 s51, s51, 0
	s_cmp_gt_u32 s53, 29
	s_cbranch_scc1 .LBB0_482
	s_mov_b32 s53, s20
	s_cmp_lt_i32 s53, 16
	s_cbranch_scc0 .LBB0_473

; #define PG8_STAGE(bufoff, gbase, voff) do { _Pragma("unroll") for (int _i = 0; _i < 2; ++_i) \
;         __builtin_amdgcn_global_load_lds((const unsigned*)((const char*)(gbase) + (voff)[_i]), (PG8_LAS unsigned*)(lds + (bufoff) + ldsw + _i * 8192), 16, 0, 0); } while (0)
; #define PG8_LDA(dst, b, h) do { _Pragma("unroll") for (int m = 0; m < 4; ++m) _Pragma("unroll") for (int k = 0; k < 2; ++k) dst[m][k] = *(const PG8_LAS bf16x8*)(lds + PG8_SA(b, h) + aoff + m * 2048 + k * 1024); } while (0)
; #define PG8_LDB(dst, b, h) do { _Pragma("unroll") for (int n = 0; n < 2; ++n) _Pragma("unroll") for (int k = 0; k < 2; ++k) dst[n][k] = *(const PG8_LAS bf16x8*)(lds + PG8_SB(b, h) + boff + n * 2048 + k * 1024); } while (0)
; #define PG8_MMA(ai, bj, At, Bt) do { __builtin_amdgcn_s_setprio(1); _Pragma("unroll") for (int m = 0; m < 4; ++m) _Pragma("unroll") for (int n = 0; n < 2; ++n) _Pragma("unroll") for (int k = 0; k < 2; ++k) \
;         acc[ai][bj][m][n] = __builtin_amdgcn_mfma_f32_16x16x32_bf16(Bt[n][k], At[m][k], acc[ai][bj][m][n], 0, 0, 0); __builtin_amdgcn_s_setprio(0); } while (0)
; #define PG8_WAIT_V(n) asm volatile("s_waitcnt vmcnt(" #n ")" ::: "memory")
; #define PG8_WAIT_L(n) asm volatile("s_waitcnt lgkmcnt(" #n ")" ::: "memory")
; template <class Epi, class Sched, bool ALIGN_EPI = false, bool SP2 = false, class Hook = NoHook, bool REVK = false>
; __device__ __forceinline__ void gemm_phase(PG8_LAS unsigned char* lds, const Gemm g, const Sched& S, const Epi& E, const Hook H = Hook()) {
;     ...
;             const char* a1 = cA + (long)(t + 1) * kstep;
;             const char* a2 = last ? nA : cA + (long)(t + 2) * kstep; const char* b2 = last ? nB : cB + (long)(t + 2) * kstep;
;             const char* a3 = a2 + kstep; const char* b3 = b2 + kstep;
;             if (last && has_next) S.a_ready(nxt);
;             if constexpr (SP2) {
;             PG8_LDB(B0, 0, 0); PG8_LDB(B1, 0, 1); PG8_SCHED; PG8_LDA(At, 0, 0); PG8_STAGE(PG8_SA(1, 1), a1 + hstep, voffA);
;             PG8_WAIT_V(8); PG8_WAIT_L(0); PG8_BAR; PG8_MMA(0, 0, At, B0); PG8_MMA(0, 1, At, B1); PG8_BAR; PG8_SCHED;
;             PG8_LDA(At, 0, 1); PG8_STAGE(PG8_SB(0, 0), b2, voffB); PG8_STAGE(PG8_SB(0, 1), b2 + hstep, voffB); PG8_STAGE(PG8_SA(0, 0), a2, voffA);
;             PG8_WAIT_V(8); PG8_WAIT_L(0); PG8_BAR; PG8_MMA(1, 0, At, B0); PG8_MMA(1, 1, At, B1); PG8_BAR; PG8_SCHED;
.LBB0_582:
	s_add_u32 s20, s22, 0xfff80080
	s_addc_u32 s21, s23, -1
	s_add_i32 s46, 0, 0x10000
	s_cmp_eq_u32 s53, 28
	s_cselect_b32 s27, s41, s21
	s_cselect_b32 s26, s42, s20
	v_add_u32_e32 v144, s46, v147
	s_cselect_b32 s21, s43, s51
	s_cselect_b32 s20, s44, s47
	s_add_i32 s58, 0, 0x14000
	ds_read_b128 v[140:143], v144
	ds_read_b128 v[152:155], v144 offset:1024
	ds_read_b128 v[156:159], v144 offset:2048
	ds_read_b128 v[160:163], v144 offset:3072
	v_add_u32_e32 v144, s58, v147
	ds_read_b128 v[164:167], v144
	ds_read_b128 v[182:185], v144 offset:1024
	ds_read_b128 v[186:189], v144 offset:2048
	ds_read_b128 v[190:193], v144 offset:3072
	v_lshl_add_u64 v[144:145], s[22:23], 0, v[136:137]
	s_add_i32 m0, s30, 0xc000
	ds_read_b128 v[194:197], v150
	ds_read_b128 v[200:203], v150 offset:1024
	ds_read_b128 v[204:207], v150 offset:2048
	ds_read_b128 v[210:213], v150 offset:3072
	ds_read_b128 v[226:229], v150 offset:4096
	ds_read_b128 v[230:233], v150 offset:5120
	ds_read_b128 v[234:237], v150 offset:6144
	ds_read_b128 v[238:241], v150 offset:7168
	global_load_lds_dwordx4 v[144:145], off
	v_lshl_add_u64 v[144:145], s[22:23], 0, v[138:139]
	s_add_i32 m0, s30, 0xe000
	s_nop 0
	global_load_lds_dwordx4 v[144:145], off
	s_waitcnt vmcnt(8)
	s_waitcnt lgkmcnt(0)
	s_setprio 1
	s_barrier
	v_mfma_f32_16x16x32_bf16 v[124:127], v[140:143], v[194:197], v[124:127]
	v_mfma_f32_16x16x32_bf16 v[120:123], v[156:159], v[194:197], v[120:123]
	v_mfma_f32_16x16x32_bf16 v[108:111], v[140:143], v[204:207], v[108:111]
	v_mfma_f32_16x16x32_bf16 v[104:107], v[156:159], v[204:207], v[104:107]
	v_mfma_f32_16x16x32_bf16 v[92:95], v[140:143], v[226:229], v[92:95]
	v_mfma_f32_16x16x32_bf16 v[88:91], v[156:159], v[226:229], v[88:91]
	v_mfma_f32_16x16x32_bf16 v[76:79], v[140:143], v[234:237], v[76:79]
	v_mfma_f32_16x16x32_bf16 v[72:75], v[156:159], v[234:237], v[72:75]
	v_mfma_f32_16x16x32_bf16 v[124:127], v[152:155], v[200:203], v[124:127]
	v_mfma_f32_16x16x32_bf16 v[120:123], v[160:163], v[200:203], v[120:123]
	v_mfma_f32_16x16x32_bf16 v[108:111], v[152:155], v[210:213], v[108:111]
	v_mfma_f32_16x16x32_bf16 v[104:107], v[160:163], v[210:213], v[104:107]
	v_mfma_f32_16x16x32_bf16 v[92:95], v[152:155], v[230:233], v[92:95]
	v_mfma_f32_16x16x32_bf16 v[88:91], v[160:163], v[230:233], v[88:91]
	v_mfma_f32_16x16x32_bf16 v[76:79], v[152:155], v[238:241], v[76:79]
	v_mfma_f32_16x16x32_bf16 v[72:75], v[160:163], v[238:241], v[72:75]
	s_setprio 0
	s_setprio 1
	v_mfma_f32_16x16x32_bf16 v[116:119], v[164:167], v[194:197], v[116:119]
	v_mfma_f32_16x16x32_bf16 v[112:115], v[186:189], v[194:197], v[112:115]
	v_mfma_f32_16x16x32_bf16 v[100:103], v[164:167], v[204:207], v[100:103]
	v_mfma_f32_16x16x32_bf16 v[96:99], v[186:189], v[204:207], v[96:99]
	v_mfma_f32_16x16x32_bf16 v[84:87], v[164:167], v[226:229], v[84:87]
	v_mfma_f32_16x16x32_bf16 v[80:83], v[186:189], v[226:229], v[80:83]
	v_mfma_f32_16x16x32_bf16 v[68:71], v[164:167], v[234:237], v[68:71]
	v_mfma_f32_16x16x32_bf16 v[64:67], v[186:189], v[234:237], v[64:67]
	v_mfma_f32_16x16x32_bf16 v[116:119], v[182:185], v[200:203], v[116:119]
	v_mfma_f32_16x16x32_bf16 v[112:115], v[190:193], v[200:203], v[112:115]
	v_mfma_f32_16x16x32_bf16 v[100:103], v[182:185], v[210:213], v[100:103]
	v_mfma_f32_16x16x32_bf16 v[96:99], v[190:193], v[210:213], v[96:99]
	v_mfma_f32_16x16x32_bf16 v[84:87], v[182:185], v[230:233], v[84:87]
	v_mfma_f32_16x16x32_bf16 v[80:83], v[190:193], v[230:233], v[80:83]
	v_mfma_f32_16x16x32_bf16 v[68:71], v[182:185], v[238:241], v[68:71]
	v_mfma_f32_16x16x32_bf16 v[64:67], v[190:193], v[238:241], v[64:67]
	s_barrier
	s_setprio 0
	s_add_i32 s46, s46, s10
	v_lshl_add_u64 v[144:145], s[20:21], 0, v[128:129]
	s_mov_b32 m0, s46
	ds_read_b128 v[194:197], v150 offset:16384
	ds_read_b128 v[200:203], v150 offset:17408
	ds_read_b128 v[204:207], v150 offset:18432
	ds_read_b128 v[210:213], v150 offset:19456
	ds_read_b128 v[226:229], v150 offset:20480
	ds_read_b128 v[230:233], v150 offset:21504
	ds_read_b128 v[234:237], v150 offset:22528
	ds_read_b128 v[238:241], v150 offset:23552
	global_load_lds_dwordx4 v[144:145], off
	s_add_i32 m0, s46, 0x2000
	s_add_u32 s56, s20, 0x80000
	v_lshl_add_u64 v[168:169], s[20:21], 0, v[130:131]
	s_addc_u32 s57, s21, 0
	s_add_i32 s46, s58, s10
	global_load_lds_dwordx4 v[168:169], off
	v_lshl_add_u64 v[214:215], s[56:57], 0, v[128:129]
	s_mov_b32 m0, s46
	v_lshl_add_u64 v[242:243], s[26:27], 0, v[132:133]
	global_load_lds_dwordx4 v[214:215], off
	v_lshl_add_u64 v[214:215], s[56:57], 0, v[130:131]
	s_add_i32 m0, s46, 0x2000
	s_nop 0
	global_load_lds_dwordx4 v[214:215], off
	v_lshl_add_u64 v[214:215], s[26:27], 0, v[134:135]
	s_mov_b32 m0, s30
	s_nop 0
	global_load_lds_dwordx4 v[214:215], off
	s_mov_b32 m0, s31
	s_nop 0
	global_load_lds_dwordx4 v[242:243], off
	s_waitcnt vmcnt(8)
	s_waitcnt lgkmcnt(0)
	s_setprio 1
	s_barrier
; #define PG8_STAGE(bufoff, gbase, voff) do { _Pragma("unroll") for (int _i = 0; _i < 2; ++_i) \
;         __builtin_amdgcn_global_load_lds((const unsigned*)((const char*)(gbase) + (voff)[_i]), (PG8_LAS unsigned*)(lds + (bufoff) + ldsw + _i * 8192), 16, 0, 0); } while (0)
; #define PG8_LDA(dst, b, h) do { _Pragma("unroll") for (int m = 0; m < 4; ++m) _Pragma("unroll") for (int k = 0; k < 2; ++k) dst[m][k] = *(const PG8_LAS bf16x8*)(lds + PG8_SA(b, h) + aoff + m * 2048 + k * 1024); } while (0)
; #define PG8_LDB(dst, b, h) do { _Pragma("unroll") for (int n = 0; n < 2; ++n) _Pragma("unroll") for (int k = 0; k < 2; ++k) dst[n][k] = *(const PG8_LAS bf16x8*)(lds + PG8_SB(b, h) + boff + n * 2048 + k * 1024); } while (0)
; #define PG8_MMA(ai, bj, At, Bt) do { __builtin_amdgcn_s_setprio(1); _Pragma("unroll") for (int m = 0; m < 4; ++m) _Pragma("unroll") for (int n = 0; n < 2; ++n) _Pragma("unroll") for (int k = 0; k < 2; ++k) \
;         acc[ai][bj][m][n] = __builtin_amdgcn_mfma_f32_16x16x32_bf16(Bt[n][k], At[m][k], acc[ai][bj][m][n], 0, 0, 0); __builtin_amdgcn_s_setprio(0); } while (0)
; #define PG8_WAIT_V(n) asm volatile("s_waitcnt vmcnt(" #n ")" ::: "memory")
; #define PG8_WAIT_L(n) asm volatile("s_waitcnt lgkmcnt(" #n ")" ::: "memory")
; #define PG8_BAR __builtin_amdgcn_s_barrier()
; #define PG8_SCHED __builtin_amdgcn_sched_barrier(0)
; template <class Epi, class Sched, bool ALIGN_EPI = false, bool SP2 = false, class Hook = NoHook, bool REVK = false>
; __device__ __forceinline__ void gemm_phase(PG8_LAS unsigned char* lds, const Gemm g, const Sched& S, const Epi& E, const Hook H = Hook()) {
;     ...
;             PG8_WAIT_V(8); PG8_WAIT_L(0); PG8_BAR; PG8_MMA(1, 0, At, B0); PG8_MMA(1, 1, At, B1); PG8_BAR; PG8_SCHED;
;             PG8_LDB(B0, 1, 0); PG8_LDB(B1, 1, 1); PG8_SCHED; PG8_LDA(At, 1, 0); PG8_STAGE(PG8_SA(0, 1), a2 + hstep, voffA);
;             PG8_WAIT_V(8); PG8_WAIT_L(0); PG8_BAR; PG8_MMA(0, 0, At, B0); PG8_MMA(0, 1, At, B1); PG8_BAR; PG8_SCHED;
	v_mfma_f32_16x16x32_bf16 v[60:63], v[140:143], v[194:197], v[60:63]
	v_mfma_f32_16x16x32_bf16 v[56:59], v[156:159], v[194:197], v[56:59]
	v_mfma_f32_16x16x32_bf16 v[44:47], v[140:143], v[204:207], v[44:47]
	v_mfma_f32_16x16x32_bf16 v[40:43], v[156:159], v[204:207], v[40:43]
	v_mfma_f32_16x16x32_bf16 v[28:31], v[140:143], v[226:229], v[28:31]
	v_mfma_f32_16x16x32_bf16 v[24:27], v[156:159], v[226:229], v[24:27]
	v_mfma_f32_16x16x32_bf16 v[12:15], v[140:143], v[234:237], v[12:15]
	v_mfma_f32_16x16x32_bf16 v[8:11], v[156:159], v[234:237], v[8:11]
	v_mfma_f32_16x16x32_bf16 v[60:63], v[152:155], v[200:203], v[60:63]
	v_mfma_f32_16x16x32_bf16 v[56:59], v[160:163], v[200:203], v[56:59]
	v_mfma_f32_16x16x32_bf16 v[44:47], v[152:155], v[210:213], v[44:47]
	v_mfma_f32_16x16x32_bf16 v[40:43], v[160:163], v[210:213], v[40:43]
	v_mfma_f32_16x16x32_bf16 v[28:31], v[152:155], v[230:233], v[28:31]
	v_mfma_f32_16x16x32_bf16 v[24:27], v[160:163], v[230:233], v[24:27]
	v_mfma_f32_16x16x32_bf16 v[12:15], v[152:155], v[238:241], v[12:15]
	v_mfma_f32_16x16x32_bf16 v[8:11], v[160:163], v[238:241], v[8:11]
	s_setprio 0
	s_setprio 1
	v_mfma_f32_16x16x32_bf16 v[52:55], v[164:167], v[194:197], v[52:55]
	v_mfma_f32_16x16x32_bf16 v[48:51], v[186:189], v[194:197], v[48:51]
	v_mfma_f32_16x16x32_bf16 v[36:39], v[164:167], v[204:207], v[36:39]
	v_mfma_f32_16x16x32_bf16 v[32:35], v[186:189], v[204:207], v[32:35]
	v_mfma_f32_16x16x32_bf16 v[20:23], v[164:167], v[226:229], v[20:23]
	v_mfma_f32_16x16x32_bf16 v[16:19], v[186:189], v[226:229], v[16:19]
	v_mfma_f32_16x16x32_bf16 v[4:7], v[164:167], v[234:237], v[4:7]
	v_mfma_f32_16x16x32_bf16 v[0:3], v[186:189], v[234:237], v[0:3]
	v_mfma_f32_16x16x32_bf16 v[52:55], v[182:185], v[200:203], v[52:55]
	v_mfma_f32_16x16x32_bf16 v[48:51], v[190:193], v[200:203], v[48:51]
	v_mfma_f32_16x16x32_bf16 v[36:39], v[182:185], v[210:213], v[36:39]
	v_mfma_f32_16x16x32_bf16 v[32:35], v[190:193], v[210:213], v[32:35]
	v_mfma_f32_16x16x32_bf16 v[20:23], v[182:185], v[230:233], v[20:23]
	v_mfma_f32_16x16x32_bf16 v[16:19], v[190:193], v[230:233], v[16:19]
	v_mfma_f32_16x16x32_bf16 v[4:7], v[182:185], v[238:241], v[4:7]
	v_mfma_f32_16x16x32_bf16 v[0:3], v[190:193], v[238:241], v[0:3]
	s_barrier
	s_setprio 0
	s_add_i32 s46, 0, 0x18000
	v_add_u32_e32 v151, s46, v147
	s_add_i32 s56, 0, 0x1c000
	ds_read_b128 v[140:143], v151
	ds_read_b128 v[152:155], v151 offset:1024
	ds_read_b128 v[156:159], v151 offset:2048
	ds_read_b128 v[160:163], v151 offset:3072
	v_add_u32_e32 v151, s56, v147
	ds_read_b128 v[164:167], v151
	ds_read_b128 v[182:185], v151 offset:1024
	ds_read_b128 v[186:189], v151 offset:2048
	ds_read_b128 v[190:193], v151 offset:3072
	s_add_u32 s26, s26, 0x80000
	s_addc_u32 s27, s27, 0
	s_mov_b32 m0, s34
	v_lshl_add_u64 v[244:245], s[26:27], 0, v[134:135]
	ds_read_b128 v[194:197], v150 offset:32768
	ds_read_b128 v[200:203], v150 offset:33792
	ds_read_b128 v[204:207], v150 offset:34816
	ds_read_b128 v[210:213], v150 offset:35840
	ds_read_b128 v[226:229], v150 offset:36864
	ds_read_b128 v[230:233], v150 offset:37888
	ds_read_b128 v[234:237], v150 offset:38912
	ds_read_b128 v[238:241], v150 offset:39936
	global_load_lds_dwordx4 v[244:245], off
	v_lshl_add_u64 v[244:245], s[26:27], 0, v[132:133]
	s_mov_b32 m0, s35
	s_nop 0
	global_load_lds_dwordx4 v[244:245], off
	s_waitcnt vmcnt(8)
	s_waitcnt lgkmcnt(0)
	s_setprio 1
	s_barrier
	v_mfma_f32_16x16x32_bf16 v[124:127], v[140:143], v[194:197], v[124:127]
	v_mfma_f32_16x16x32_bf16 v[120:123], v[156:159], v[194:197], v[120:123]
	v_mfma_f32_16x16x32_bf16 v[108:111], v[140:143], v[204:207], v[108:111]
	v_mfma_f32_16x16x32_bf16 v[104:107], v[156:159], v[204:207], v[104:107]
	v_mfma_f32_16x16x32_bf16 v[92:95], v[140:143], v[226:229], v[92:95]
	v_mfma_f32_16x16x32_bf16 v[88:91], v[156:159], v[226:229], v[88:91]
	v_mfma_f32_16x16x32_bf16 v[76:79], v[140:143], v[234:237], v[76:79]
	v_mfma_f32_16x16x32_bf16 v[72:75], v[156:159], v[234:237], v[72:75]
	v_mfma_f32_16x16x32_bf16 v[124:127], v[152:155], v[200:203], v[124:127]
	v_mfma_f32_16x16x32_bf16 v[120:123], v[160:163], v[200:203], v[120:123]
	v_mfma_f32_16x16x32_bf16 v[108:111], v[152:155], v[210:213], v[108:111]
	v_mfma_f32_16x16x32_bf16 v[104:107], v[160:163], v[210:213], v[104:107]
	v_mfma_f32_16x16x32_bf16 v[92:95], v[152:155], v[230:233], v[92:95]
	v_mfma_f32_16x16x32_bf16 v[88:91], v[160:163], v[230:233], v[88:91]
	v_mfma_f32_16x16x32_bf16 v[76:79], v[152:155], v[238:241], v[76:79]
	v_mfma_f32_16x16x32_bf16 v[72:75], v[160:163], v[238:241], v[72:75]
	s_setprio 0
	s_setprio 1
	v_mfma_f32_16x16x32_bf16 v[116:119], v[164:167], v[194:197], v[116:119]
	v_mfma_f32_16x16x32_bf16 v[112:115], v[186:189], v[194:197], v[112:115]
	v_mfma_f32_16x16x32_bf16 v[100:103], v[164:167], v[204:207], v[100:103]
	v_mfma_f32_16x16x32_bf16 v[96:99], v[186:189], v[204:207], v[96:99]
	v_mfma_f32_16x16x32_bf16 v[84:87], v[164:167], v[226:229], v[84:87]
	v_mfma_f32_16x16x32_bf16 v[80:83], v[186:189], v[226:229], v[80:83]
	v_mfma_f32_16x16x32_bf16 v[68:71], v[164:167], v[234:237], v[68:71]
	v_mfma_f32_16x16x32_bf16 v[64:67], v[186:189], v[234:237], v[64:67]
	v_mfma_f32_16x16x32_bf16 v[116:119], v[182:185], v[200:203], v[116:119]
	v_mfma_f32_16x16x32_bf16 v[112:115], v[190:193], v[200:203], v[112:115]
	v_mfma_f32_16x16x32_bf16 v[100:103], v[182:185], v[210:213], v[100:103]
	v_mfma_f32_16x16x32_bf16 v[96:99], v[190:193], v[210:213], v[96:99]
	v_mfma_f32_16x16x32_bf16 v[84:87], v[182:185], v[230:233], v[84:87]
	v_mfma_f32_16x16x32_bf16 v[80:83], v[190:193], v[230:233], v[80:83]
	v_mfma_f32_16x16x32_bf16 v[68:71], v[182:185], v[238:241], v[68:71]
	v_mfma_f32_16x16x32_bf16 v[64:67], v[190:193], v[238:241], v[64:67]
	s_barrier
; #define PG8_STAGE(bufoff, gbase, voff) do { _Pragma("unroll") for (int _i = 0; _i < 2; ++_i) \
;         __builtin_amdgcn_global_load_lds((const unsigned*)((const char*)(gbase) + (voff)[_i]), (PG8_LAS unsigned*)(lds + (bufoff) + ldsw + _i * 8192), 16, 0, 0); } while (0)
; #define PG8_LDA(dst, b, h) do { _Pragma("unroll") for (int m = 0; m < 4; ++m) _Pragma("unroll") for (int k = 0; k < 2; ++k) dst[m][k] = *(const PG8_LAS bf16x8*)(lds + PG8_SA(b, h) + aoff + m * 2048 + k * 1024); } while (0)
; #define PG8_MMA(ai, bj, At, Bt) do { __builtin_amdgcn_s_setprio(1); _Pragma("unroll") for (int m = 0; m < 4; ++m) _Pragma("unroll") for (int n = 0; n < 2; ++n) _Pragma("unroll") for (int k = 0; k < 2; ++k) \
;         acc[ai][bj][m][n] = __builtin_amdgcn_mfma_f32_16x16x32_bf16(Bt[n][k], At[m][k], acc[ai][bj][m][n], 0, 0, 0); __builtin_amdgcn_s_setprio(0); } while (0)
; #define PG8_WAIT_V(n) asm volatile("s_waitcnt vmcnt(" #n ")" ::: "memory")
; #define PG8_WAIT_L(n) asm volatile("s_waitcnt lgkmcnt(" #n ")" ::: "memory")
; #define PG8_BAR __builtin_amdgcn_s_barrier()
; #define PG8_SCHED __builtin_amdgcn_sched_barrier(0)
; template <class Epi, class Sched, bool ALIGN_EPI = false, bool SP2 = false, class Hook = NoHook, bool REVK = false>
; __device__ __forceinline__ void gemm_phase(PG8_LAS unsigned char* lds, const Gemm g, const Sched& S, const Epi& E, const Hook H = Hook()) {
;     ...
;             PG8_WAIT_V(8); PG8_WAIT_L(0); PG8_BAR; PG8_MMA(0, 0, At, B0); PG8_MMA(0, 1, At, B1); PG8_BAR; PG8_SCHED;
;             PG8_LDA(At, 1, 1); PG8_STAGE(PG8_SB(1, 0), b3, voffB); PG8_STAGE(PG8_SB(1, 1), b3 + hstep, voffB); PG8_STAGE(PG8_SA(1, 0), a3, voffA);
;             PG8_WAIT_V(8); PG8_WAIT_L(0); PG8_BAR; PG8_MMA(1, 0, At, B0); PG8_MMA(1, 1, At, B1); PG8_BAR; PG8_SCHED;
	s_setprio 0
	s_add_i32 s26, s46, s10
	v_lshl_add_u64 v[144:145], v[144:145], 0, s[64:65]
	s_mov_b32 m0, s26
	ds_read_b128 v[194:197], v150 offset:49152
	ds_read_b128 v[200:203], v150 offset:50176
	ds_read_b128 v[204:207], v150 offset:51200
	ds_read_b128 v[210:213], v150 offset:52224
	ds_read_b128 v[226:229], v150 offset:53248
	ds_read_b128 v[230:233], v150 offset:54272
	ds_read_b128 v[234:237], v150 offset:55296
	ds_read_b128 v[238:241], v150 offset:56320
	global_load_lds_dwordx4 v[144:145], off
	s_add_i32 m0, s26, 0x2000
	s_add_u32 s20, s20, 0x80080
	v_lshl_add_u64 v[144:145], v[168:169], 0, s[64:65]
	s_addc_u32 s21, s21, 0
	s_add_i32 s26, s56, s10
	global_load_lds_dwordx4 v[144:145], off
	v_lshl_add_u64 v[144:145], s[20:21], 0, v[128:129]
	s_mov_b32 m0, s26
	s_nop 0
	global_load_lds_dwordx4 v[144:145], off
	v_lshl_add_u64 v[144:145], s[20:21], 0, v[130:131]
	s_add_i32 m0, s26, 0x2000
	s_nop 0
	global_load_lds_dwordx4 v[144:145], off
	v_lshl_add_u64 v[144:145], v[214:215], 0, s[64:65]
	s_mov_b32 m0, s36
	s_nop 0
	global_load_lds_dwordx4 v[144:145], off
	v_lshl_add_u64 v[144:145], v[242:243], 0, s[64:65]
	s_mov_b32 m0, s38
	s_nop 0
	global_load_lds_dwordx4 v[144:145], off
	s_waitcnt vmcnt(8)
	s_waitcnt lgkmcnt(0)
	s_setprio 1
	s_barrier
	v_mfma_f32_16x16x32_bf16 v[60:63], v[140:143], v[194:197], v[60:63]
	v_mfma_f32_16x16x32_bf16 v[56:59], v[156:159], v[194:197], v[56:59]
	v_mfma_f32_16x16x32_bf16 v[44:47], v[140:143], v[204:207], v[44:47]
	v_mfma_f32_16x16x32_bf16 v[40:43], v[156:159], v[204:207], v[40:43]
	v_mfma_f32_16x16x32_bf16 v[28:31], v[140:143], v[226:229], v[28:31]
	v_mfma_f32_16x16x32_bf16 v[24:27], v[156:159], v[226:229], v[24:27]
	v_mfma_f32_16x16x32_bf16 v[12:15], v[140:143], v[234:237], v[12:15]
	v_mfma_f32_16x16x32_bf16 v[8:11], v[156:159], v[234:237], v[8:11]
	v_mfma_f32_16x16x32_bf16 v[60:63], v[152:155], v[200:203], v[60:63]
	v_mfma_f32_16x16x32_bf16 v[56:59], v[160:163], v[200:203], v[56:59]
	v_mfma_f32_16x16x32_bf16 v[44:47], v[152:155], v[210:213], v[44:47]
	v_mfma_f32_16x16x32_bf16 v[40:43], v[160:163], v[210:213], v[40:43]
	v_mfma_f32_16x16x32_bf16 v[28:31], v[152:155], v[230:233], v[28:31]
	v_mfma_f32_16x16x32_bf16 v[24:27], v[160:163], v[230:233], v[24:27]
	v_mfma_f32_16x16x32_bf16 v[12:15], v[152:155], v[238:241], v[12:15]
	v_mfma_f32_16x16x32_bf16 v[8:11], v[160:163], v[238:241], v[8:11]
	s_setprio 0
	s_setprio 1
	v_mfma_f32_16x16x32_bf16 v[52:55], v[164:167], v[194:197], v[52:55]
	v_mfma_f32_16x16x32_bf16 v[48:51], v[186:189], v[194:197], v[48:51]
	v_mfma_f32_16x16x32_bf16 v[36:39], v[164:167], v[204:207], v[36:39]
	v_mfma_f32_16x16x32_bf16 v[32:35], v[186:189], v[204:207], v[32:35]
	v_mfma_f32_16x16x32_bf16 v[20:23], v[164:167], v[226:229], v[20:23]
	v_mfma_f32_16x16x32_bf16 v[16:19], v[186:189], v[226:229], v[16:19]
	v_mfma_f32_16x16x32_bf16 v[4:7], v[164:167], v[234:237], v[4:7]
	v_mfma_f32_16x16x32_bf16 v[0:3], v[186:189], v[234:237], v[0:3]
	v_mfma_f32_16x16x32_bf16 v[52:55], v[182:185], v[200:203], v[52:55]
	v_mfma_f32_16x16x32_bf16 v[48:51], v[190:193], v[200:203], v[48:51]
	v_mfma_f32_16x16x32_bf16 v[36:39], v[182:185], v[210:213], v[36:39]
	v_mfma_f32_16x16x32_bf16 v[32:35], v[190:193], v[210:213], v[32:35]
	v_mfma_f32_16x16x32_bf16 v[20:23], v[182:185], v[230:233], v[20:23]
	v_mfma_f32_16x16x32_bf16 v[16:19], v[190:193], v[230:233], v[16:19]
	v_mfma_f32_16x16x32_bf16 v[4:7], v[182:185], v[238:241], v[4:7]
	v_mfma_f32_16x16x32_bf16 v[0:3], v[190:193], v[238:241], v[0:3]
	s_barrier
	s_setprio 0
	s_add_i32 s53, s53, 2
	s_add_u32 s22, s22, 0x100
	s_addc_u32 s23, s23, 0
	s_add_u32 s47, s47, 0x100
	s_addc_u32 s51, s51, 0
	s_cmp_gt_u32 s53, 29
	s_cbranch_scc0 .LBB0_582
	s_and_b64 vcc, exec, s[82:83]
	s_cbranch_vccz .LBB0_585
	s_barrier

; #define PG8_STAGE(bufoff, gbase, voff) do { _Pragma("unroll") for (int _i = 0; _i < 2; ++_i) \
;         __builtin_amdgcn_global_load_lds((const unsigned*)((const char*)(gbase) + (voff)[_i]), (PG8_LAS unsigned*)(lds + (bufoff) + ldsw + _i * 8192), 16, 0, 0); } while (0)
; #define PG8_LDA(dst, b, h) do { _Pragma("unroll") for (int m = 0; m < 4; ++m) _Pragma("unroll") for (int k = 0; k < 2; ++k) dst[m][k] = *(const PG8_LAS bf16x8*)(lds + PG8_SA(b, h) + aoff + m * 2048 + k * 1024); } while (0)
; #define PG8_LDB(dst, b, h) do { _Pragma("unroll") for (int n = 0; n < 2; ++n) _Pragma("unroll") for (int k = 0; k < 2; ++k) dst[n][k] = *(const PG8_LAS bf16x8*)(lds + PG8_SB(b, h) + boff + n * 2048 + k * 1024); } while (0)
; #define PG8_MMA(ai, bj, At, Bt) do { __builtin_amdgcn_s_setprio(1); _Pragma("unroll") for (int m = 0; m < 4; ++m) _Pragma("unroll") for (int n = 0; n < 2; ++n) _Pragma("unroll") for (int k = 0; k < 2; ++k) \
;         acc[ai][bj][m][n] = __builtin_amdgcn_mfma_f32_16x16x32_bf16(Bt[n][k], At[m][k], acc[ai][bj][m][n], 0, 0, 0); __builtin_amdgcn_s_setprio(0); } while (0)
; #define PG8_WAIT_V(n) asm volatile("s_waitcnt vmcnt(" #n ")" ::: "memory")
; #define PG8_WAIT_L(n) asm volatile("s_waitcnt lgkmcnt(" #n ")" ::: "memory")
; template <class Epi, class Sched, bool ALIGN_EPI = false, bool SP2 = false, class Hook = NoHook, bool REVK = false>
; __device__ __forceinline__ void gemm_phase(PG8_LAS unsigned char* lds, const Gemm g, const Sched& S, const Epi& E, const Hook H = Hook()) {
;     ...
;             const char* a1 = cA + (long)(t + 1) * kstep;
;             const char* a2 = last ? nA : cA + (long)(t + 2) * kstep; const char* b2 = last ? nB : cB + (long)(t + 2) * kstep;
;             const char* a3 = a2 + kstep; const char* b3 = b2 + kstep;
;             if (last && has_next) S.a_ready(nxt);
;             if constexpr (SP2) {
;             PG8_LDB(B0, 0, 0); PG8_LDB(B1, 0, 1); PG8_SCHED; PG8_LDA(At, 0, 0); PG8_STAGE(PG8_SA(1, 1), a1 + hstep, voffA);
;             PG8_WAIT_V(8); PG8_WAIT_L(0); PG8_BAR; PG8_MMA(0, 0, At, B0); PG8_MMA(0, 1, At, B1); PG8_BAR; PG8_SCHED;
;             PG8_LDA(At, 0, 1); PG8_STAGE(PG8_SB(0, 0), b2, voffB); PG8_STAGE(PG8_SB(0, 1), b2 + hstep, voffB); PG8_STAGE(PG8_SA(0, 0), a2, voffA);
;             PG8_WAIT_V(8); PG8_WAIT_L(0); PG8_BAR; PG8_MMA(1, 0, At, B0); PG8_MMA(1, 1, At, B1); PG8_BAR; PG8_SCHED;
.LBB0_654:
	s_or_b32 s54, s42, 1
	s_lshl_b64 s[46:47], s[54:55], 7
	s_sub_u32 s44, 0, s46
	s_subb_u32 s46, 0, s47
	s_add_u32 s44, s94, s44
	s_addc_u32 s47, s95, s46
	s_add_i32 s51, 0, 0x10000
	s_add_i32 s53, 0, 0x14000
	v_add_u32_e32 v142, s51, v195
	v_add_u32_e32 v158, s53, v195
	ds_read_b128 v[124:127], v142
	ds_read_b128 v[134:137], v142 offset:1024
	ds_read_b128 v[138:141], v142 offset:2048
	ds_read_b128 v[142:145], v142 offset:3072
	ds_read_b128 v[146:149], v158
	ds_read_b128 v[150:153], v158 offset:1024
	ds_read_b128 v[154:157], v158 offset:2048
	ds_read_b128 v[158:161], v158 offset:3072
	s_add_u32 s46, s44, 0x200000
	s_addc_u32 s47, s47, 0
	v_lshl_add_u64 v[168:169], s[46:47], 0, v[166:167]
	s_add_i32 m0, s34, 0xc000
	ds_read_b128 v[182:185], v197
	ds_read_b128 v[186:189], v197 offset:1024
	ds_read_b128 v[190:193], v197 offset:2048
	ds_read_b128 v[200:203], v197 offset:3072
	ds_read_b128 v[204:207], v197 offset:4096
	ds_read_b128 v[210:213], v197 offset:5120
	ds_read_b128 v[226:229], v197 offset:6144
	ds_read_b128 v[230:233], v197 offset:7168
	global_load_lds_dwordx4 v[168:169], off
	v_lshl_add_u64 v[168:169], s[46:47], 0, v[164:165]
	s_add_i32 m0, s34, 0xe000
	s_nop 0
	global_load_lds_dwordx4 v[168:169], off
	s_waitcnt vmcnt(8)
	s_waitcnt lgkmcnt(0)
	s_setprio 1
	s_barrier
	v_mfma_f32_16x16x32_bf16 v[130:133], v[124:127], v[182:185], v[130:133]
	v_mfma_f32_16x16x32_bf16 v[120:123], v[138:141], v[182:185], v[120:123]
	v_mfma_f32_16x16x32_bf16 v[108:111], v[124:127], v[190:193], v[108:111]
	v_mfma_f32_16x16x32_bf16 v[104:107], v[138:141], v[190:193], v[104:107]
	v_mfma_f32_16x16x32_bf16 v[92:95], v[124:127], v[204:207], v[92:95]
	v_mfma_f32_16x16x32_bf16 v[88:91], v[138:141], v[204:207], v[88:91]
	v_mfma_f32_16x16x32_bf16 v[76:79], v[124:127], v[226:229], v[76:79]
	v_mfma_f32_16x16x32_bf16 v[72:75], v[138:141], v[226:229], v[72:75]
	v_mfma_f32_16x16x32_bf16 v[130:133], v[134:137], v[186:189], v[130:133]
	v_mfma_f32_16x16x32_bf16 v[120:123], v[142:145], v[186:189], v[120:123]
	v_mfma_f32_16x16x32_bf16 v[108:111], v[134:137], v[200:203], v[108:111]
	v_mfma_f32_16x16x32_bf16 v[104:107], v[142:145], v[200:203], v[104:107]
	v_mfma_f32_16x16x32_bf16 v[92:95], v[134:137], v[210:213], v[92:95]
	v_mfma_f32_16x16x32_bf16 v[88:91], v[142:145], v[210:213], v[88:91]
	v_mfma_f32_16x16x32_bf16 v[76:79], v[134:137], v[230:233], v[76:79]
	v_mfma_f32_16x16x32_bf16 v[72:75], v[142:145], v[230:233], v[72:75]
	s_setprio 0
	s_setprio 1
	v_mfma_f32_16x16x32_bf16 v[116:119], v[146:149], v[182:185], v[116:119]
	v_mfma_f32_16x16x32_bf16 v[112:115], v[154:157], v[182:185], v[112:115]
	v_mfma_f32_16x16x32_bf16 v[100:103], v[146:149], v[190:193], v[100:103]
	v_mfma_f32_16x16x32_bf16 v[96:99], v[154:157], v[190:193], v[96:99]
	v_mfma_f32_16x16x32_bf16 v[84:87], v[146:149], v[204:207], v[84:87]
	v_mfma_f32_16x16x32_bf16 v[80:83], v[154:157], v[204:207], v[80:83]
	v_mfma_f32_16x16x32_bf16 v[68:71], v[146:149], v[226:229], v[68:71]
	v_mfma_f32_16x16x32_bf16 v[64:67], v[154:157], v[226:229], v[64:67]
	v_mfma_f32_16x16x32_bf16 v[116:119], v[150:153], v[186:189], v[116:119]
	v_mfma_f32_16x16x32_bf16 v[112:115], v[158:161], v[186:189], v[112:115]
	v_mfma_f32_16x16x32_bf16 v[100:103], v[150:153], v[200:203], v[100:103]
	v_mfma_f32_16x16x32_bf16 v[96:99], v[158:161], v[200:203], v[96:99]
	v_mfma_f32_16x16x32_bf16 v[84:87], v[150:153], v[210:213], v[84:87]
	v_mfma_f32_16x16x32_bf16 v[80:83], v[158:161], v[210:213], v[80:83]
	v_mfma_f32_16x16x32_bf16 v[68:71], v[150:153], v[230:233], v[68:71]
	v_mfma_f32_16x16x32_bf16 v[64:67], v[158:161], v[230:233], v[64:67]
	s_barrier
	s_setprio 0
	s_add_i32 s44, s51, s31
	v_lshl_add_u64 v[168:169], s[20:21], 0, v[128:129]
	s_mov_b32 m0, s44
	ds_read_b128 v[182:185], v197 offset:16384
	ds_read_b128 v[186:189], v197 offset:17408
	ds_read_b128 v[190:193], v197 offset:18432
	ds_read_b128 v[200:203], v197 offset:19456
	ds_read_b128 v[204:207], v197 offset:20480
	ds_read_b128 v[210:213], v197 offset:21504
	ds_read_b128 v[226:229], v197 offset:22528
	ds_read_b128 v[230:233], v197 offset:23552
	global_load_lds_dwordx4 v[168:169], off
	s_add_i32 m0, s44, 0x2000
	s_add_u32 s46, s20, 0x200000
	v_lshl_add_u64 v[214:215], s[20:21], 0, v[162:163]
	s_addc_u32 s47, s21, 0
	s_add_i32 s44, s53, s31
	global_load_lds_dwordx4 v[214:215], off
	v_lshl_add_u64 v[234:235], s[46:47], 0, v[128:129]
	s_mov_b32 m0, s44
	v_lshl_add_u64 v[236:237], s[26:27], 0, v[164:165]
	global_load_lds_dwordx4 v[234:235], off
	v_lshl_add_u64 v[234:235], s[46:47], 0, v[162:163]
	s_add_i32 m0, s44, 0x2000
	s_nop 0
	global_load_lds_dwordx4 v[234:235], off
	v_lshl_add_u64 v[234:235], s[26:27], 0, v[166:167]
	s_mov_b32 m0, s34
	s_nop 0
	global_load_lds_dwordx4 v[234:235], off
	s_mov_b32 m0, s35
	s_nop 0
	global_load_lds_dwordx4 v[236:237], off
	s_waitcnt vmcnt(8)
	s_waitcnt lgkmcnt(0)
	s_setprio 1
	s_barrier
; #define PG8_STAGE(bufoff, gbase, voff) do { _Pragma("unroll") for (int _i = 0; _i < 2; ++_i) \
;         __builtin_amdgcn_global_load_lds((const unsigned*)((const char*)(gbase) + (voff)[_i]), (PG8_LAS unsigned*)(lds + (bufoff) + ldsw + _i * 8192), 16, 0, 0); } while (0)
; #define PG8_LDA(dst, b, h) do { _Pragma("unroll") for (int m = 0; m < 4; ++m) _Pragma("unroll") for (int k = 0; k < 2; ++k) dst[m][k] = *(const PG8_LAS bf16x8*)(lds + PG8_SA(b, h) + aoff + m * 2048 + k * 1024); } while (0)
; #define PG8_LDB(dst, b, h) do { _Pragma("unroll") for (int n = 0; n < 2; ++n) _Pragma("unroll") for (int k = 0; k < 2; ++k) dst[n][k] = *(const PG8_LAS bf16x8*)(lds + PG8_SB(b, h) + boff + n * 2048 + k * 1024); } while (0)
; #define PG8_MMA(ai, bj, At, Bt) do { __builtin_amdgcn_s_setprio(1); _Pragma("unroll") for (int m = 0; m < 4; ++m) _Pragma("unroll") for (int n = 0; n < 2; ++n) _Pragma("unroll") for (int k = 0; k < 2; ++k) \
;         acc[ai][bj][m][n] = __builtin_amdgcn_mfma_f32_16x16x32_bf16(Bt[n][k], At[m][k], acc[ai][bj][m][n], 0, 0, 0); __builtin_amdgcn_s_setprio(0); } while (0)
; #define PG8_WAIT_V(n) asm volatile("s_waitcnt vmcnt(" #n ")" ::: "memory")
; #define PG8_WAIT_L(n) asm volatile("s_waitcnt lgkmcnt(" #n ")" ::: "memory")
; #define PG8_BAR __builtin_amdgcn_s_barrier()
; #define PG8_SCHED __builtin_amdgcn_sched_barrier(0)
; template <class Epi, class Sched, bool ALIGN_EPI = false, bool SP2 = false, class Hook = NoHook, bool REVK = false>
; __device__ __forceinline__ void gemm_phase(PG8_LAS unsigned char* lds, const Gemm g, const Sched& S, const Epi& E, const Hook H = Hook()) {
;     ...
;             PG8_WAIT_V(8); PG8_WAIT_L(0); PG8_BAR; PG8_MMA(1, 0, At, B0); PG8_MMA(1, 1, At, B1); PG8_BAR; PG8_SCHED;
;             PG8_LDB(B0, 1, 0); PG8_LDB(B1, 1, 1); PG8_SCHED; PG8_LDA(At, 1, 0); PG8_STAGE(PG8_SA(0, 1), a2 + hstep, voffA);
;             PG8_WAIT_V(8); PG8_WAIT_L(0); PG8_BAR; PG8_MMA(0, 0, At, B0); PG8_MMA(0, 1, At, B1); PG8_BAR; PG8_SCHED;
	v_mfma_f32_16x16x32_bf16 v[60:63], v[124:127], v[182:185], v[60:63]
	v_mfma_f32_16x16x32_bf16 v[56:59], v[138:141], v[182:185], v[56:59]
	v_mfma_f32_16x16x32_bf16 v[44:47], v[124:127], v[190:193], v[44:47]
	v_mfma_f32_16x16x32_bf16 v[40:43], v[138:141], v[190:193], v[40:43]
	v_mfma_f32_16x16x32_bf16 v[28:31], v[124:127], v[204:207], v[28:31]
	v_mfma_f32_16x16x32_bf16 v[24:27], v[138:141], v[204:207], v[24:27]
	v_mfma_f32_16x16x32_bf16 v[12:15], v[124:127], v[226:229], v[12:15]
	v_mfma_f32_16x16x32_bf16 v[8:11], v[138:141], v[226:229], v[8:11]
	v_mfma_f32_16x16x32_bf16 v[60:63], v[134:137], v[186:189], v[60:63]
	v_mfma_f32_16x16x32_bf16 v[56:59], v[142:145], v[186:189], v[56:59]
	v_mfma_f32_16x16x32_bf16 v[44:47], v[134:137], v[200:203], v[44:47]
	v_mfma_f32_16x16x32_bf16 v[40:43], v[142:145], v[200:203], v[40:43]
	v_mfma_f32_16x16x32_bf16 v[28:31], v[134:137], v[210:213], v[28:31]
	v_mfma_f32_16x16x32_bf16 v[24:27], v[142:145], v[210:213], v[24:27]
	v_mfma_f32_16x16x32_bf16 v[12:15], v[134:137], v[230:233], v[12:15]
	v_mfma_f32_16x16x32_bf16 v[8:11], v[142:145], v[230:233], v[8:11]
	s_setprio 0
	s_setprio 1
	v_mfma_f32_16x16x32_bf16 v[52:55], v[146:149], v[182:185], v[52:55]
	v_mfma_f32_16x16x32_bf16 v[48:51], v[154:157], v[182:185], v[48:51]
	v_mfma_f32_16x16x32_bf16 v[36:39], v[146:149], v[190:193], v[36:39]
	v_mfma_f32_16x16x32_bf16 v[32:35], v[154:157], v[190:193], v[32:35]
	v_mfma_f32_16x16x32_bf16 v[20:23], v[146:149], v[204:207], v[20:23]
	v_mfma_f32_16x16x32_bf16 v[16:19], v[154:157], v[204:207], v[16:19]
	v_mfma_f32_16x16x32_bf16 v[4:7], v[146:149], v[226:229], v[4:7]
	v_mfma_f32_16x16x32_bf16 v[0:3], v[154:157], v[226:229], v[0:3]
	v_mfma_f32_16x16x32_bf16 v[52:55], v[150:153], v[186:189], v[52:55]
	v_mfma_f32_16x16x32_bf16 v[48:51], v[158:161], v[186:189], v[48:51]
	v_mfma_f32_16x16x32_bf16 v[36:39], v[150:153], v[200:203], v[36:39]
	v_mfma_f32_16x16x32_bf16 v[32:35], v[158:161], v[200:203], v[32:35]
	v_mfma_f32_16x16x32_bf16 v[20:23], v[150:153], v[210:213], v[20:23]
	v_mfma_f32_16x16x32_bf16 v[16:19], v[158:161], v[210:213], v[16:19]
	v_mfma_f32_16x16x32_bf16 v[4:7], v[150:153], v[230:233], v[4:7]
	v_mfma_f32_16x16x32_bf16 v[0:3], v[158:161], v[230:233], v[0:3]
	s_barrier
	s_setprio 0
	s_add_i32 s44, 0, 0x18000
	s_add_i32 s46, 0, 0x1c000
	v_add_u32_e32 v142, s44, v195
	v_add_u32_e32 v158, s46, v195
	ds_read_b128 v[124:127], v142
	ds_read_b128 v[134:137], v142 offset:1024
	ds_read_b128 v[138:141], v142 offset:2048
	ds_read_b128 v[142:145], v142 offset:3072
	ds_read_b128 v[146:149], v158
	ds_read_b128 v[150:153], v158 offset:1024
	ds_read_b128 v[154:157], v158 offset:2048
	ds_read_b128 v[158:161], v158 offset:3072
	s_add_u32 s26, s26, 0x200000
	s_addc_u32 s27, s27, 0
	s_mov_b32 m0, s36
	v_lshl_add_u64 v[238:239], s[26:27], 0, v[166:167]
	ds_read_b128 v[182:185], v197 offset:32768
	ds_read_b128 v[186:189], v197 offset:33792
	ds_read_b128 v[190:193], v197 offset:34816
	ds_read_b128 v[200:203], v197 offset:35840
	ds_read_b128 v[204:207], v197 offset:36864
	ds_read_b128 v[210:213], v197 offset:37888
	ds_read_b128 v[226:229], v197 offset:38912
	ds_read_b128 v[230:233], v197 offset:39936
	global_load_lds_dwordx4 v[238:239], off
	v_lshl_add_u64 v[238:239], s[26:27], 0, v[164:165]
	s_mov_b32 m0, s38
	s_nop 0
	global_load_lds_dwordx4 v[238:239], off
	s_waitcnt vmcnt(8)
	s_waitcnt lgkmcnt(0)
	s_setprio 1
	s_barrier
	v_mfma_f32_16x16x32_bf16 v[130:133], v[124:127], v[182:185], v[130:133]
	v_mfma_f32_16x16x32_bf16 v[120:123], v[138:141], v[182:185], v[120:123]
	v_mfma_f32_16x16x32_bf16 v[108:111], v[124:127], v[190:193], v[108:111]
	v_mfma_f32_16x16x32_bf16 v[104:107], v[138:141], v[190:193], v[104:107]
	v_mfma_f32_16x16x32_bf16 v[92:95], v[124:127], v[204:207], v[92:95]
	v_mfma_f32_16x16x32_bf16 v[88:91], v[138:141], v[204:207], v[88:91]
	v_mfma_f32_16x16x32_bf16 v[76:79], v[124:127], v[226:229], v[76:79]
	v_mfma_f32_16x16x32_bf16 v[72:75], v[138:141], v[226:229], v[72:75]
	v_mfma_f32_16x16x32_bf16 v[130:133], v[134:137], v[186:189], v[130:133]
	v_mfma_f32_16x16x32_bf16 v[120:123], v[142:145], v[186:189], v[120:123]
	v_mfma_f32_16x16x32_bf16 v[108:111], v[134:137], v[200:203], v[108:111]
	v_mfma_f32_16x16x32_bf16 v[104:107], v[142:145], v[200:203], v[104:107]
	v_mfma_f32_16x16x32_bf16 v[92:95], v[134:137], v[210:213], v[92:95]
	v_mfma_f32_16x16x32_bf16 v[88:91], v[142:145], v[210:213], v[88:91]
	v_mfma_f32_16x16x32_bf16 v[76:79], v[134:137], v[230:233], v[76:79]
	v_mfma_f32_16x16x32_bf16 v[72:75], v[142:145], v[230:233], v[72:75]
	s_setprio 0
	s_setprio 1
	v_mfma_f32_16x16x32_bf16 v[116:119], v[146:149], v[182:185], v[116:119]
	v_mfma_f32_16x16x32_bf16 v[112:115], v[154:157], v[182:185], v[112:115]
	v_mfma_f32_16x16x32_bf16 v[100:103], v[146:149], v[190:193], v[100:103]
	v_mfma_f32_16x16x32_bf16 v[96:99], v[154:157], v[190:193], v[96:99]
	v_mfma_f32_16x16x32_bf16 v[84:87], v[146:149], v[204:207], v[84:87]
	v_mfma_f32_16x16x32_bf16 v[80:83], v[154:157], v[204:207], v[80:83]
	v_mfma_f32_16x16x32_bf16 v[68:71], v[146:149], v[226:229], v[68:71]
	v_mfma_f32_16x16x32_bf16 v[64:67], v[154:157], v[226:229], v[64:67]
	v_mfma_f32_16x16x32_bf16 v[116:119], v[150:153], v[186:189], v[116:119]
	v_mfma_f32_16x16x32_bf16 v[112:115], v[158:161], v[186:189], v[112:115]
	v_mfma_f32_16x16x32_bf16 v[100:103], v[150:153], v[200:203], v[100:103]
	v_mfma_f32_16x16x32_bf16 v[96:99], v[158:161], v[200:203], v[96:99]
	v_mfma_f32_16x16x32_bf16 v[84:87], v[150:153], v[210:213], v[84:87]
	v_mfma_f32_16x16x32_bf16 v[80:83], v[158:161], v[210:213], v[80:83]
	v_mfma_f32_16x16x32_bf16 v[68:71], v[150:153], v[230:233], v[68:71]
	v_mfma_f32_16x16x32_bf16 v[64:67], v[158:161], v[230:233], v[64:67]
	s_barrier
; #define PG8_STAGE(bufoff, gbase, voff) do { _Pragma("unroll") for (int _i = 0; _i < 2; ++_i) \
;         __builtin_amdgcn_global_load_lds((const unsigned*)((const char*)(gbase) + (voff)[_i]), (PG8_LAS unsigned*)(lds + (bufoff) + ldsw + _i * 8192), 16, 0, 0); } while (0)
; #define PG8_LDA(dst, b, h) do { _Pragma("unroll") for (int m = 0; m < 4; ++m) _Pragma("unroll") for (int k = 0; k < 2; ++k) dst[m][k] = *(const PG8_LAS bf16x8*)(lds + PG8_SA(b, h) + aoff + m * 2048 + k * 1024); } while (0)
; #define PG8_MMA(ai, bj, At, Bt) do { __builtin_amdgcn_s_setprio(1); _Pragma("unroll") for (int m = 0; m < 4; ++m) _Pragma("unroll") for (int n = 0; n < 2; ++n) _Pragma("unroll") for (int k = 0; k < 2; ++k) \
;         acc[ai][bj][m][n] = __builtin_amdgcn_mfma_f32_16x16x32_bf16(Bt[n][k], At[m][k], acc[ai][bj][m][n], 0, 0, 0); __builtin_amdgcn_s_setprio(0); } while (0)
; #define PG8_WAIT_V(n) asm volatile("s_waitcnt vmcnt(" #n ")" ::: "memory")
; #define PG8_WAIT_L(n) asm volatile("s_waitcnt lgkmcnt(" #n ")" ::: "memory")
; #define PG8_BAR __builtin_amdgcn_s_barrier()
; #define PG8_SCHED __builtin_amdgcn_sched_barrier(0)
; template <class Epi, class Sched, bool ALIGN_EPI = false, bool SP2 = false, class Hook = NoHook, bool REVK = false>
; __device__ __forceinline__ void gemm_phase(PG8_LAS unsigned char* lds, const Gemm g, const Sched& S, const Epi& E, const Hook H = Hook()) {
;     ...
;             PG8_WAIT_V(8); PG8_WAIT_L(0); PG8_BAR; PG8_MMA(0, 0, At, B0); PG8_MMA(0, 1, At, B1); PG8_BAR; PG8_SCHED;
;             PG8_LDA(At, 1, 1); PG8_STAGE(PG8_SB(1, 0), b3, voffB); PG8_STAGE(PG8_SB(1, 1), b3 + hstep, voffB); PG8_STAGE(PG8_SA(1, 0), a3, voffA);
;             PG8_WAIT_V(8); PG8_WAIT_L(0); PG8_BAR; PG8_MMA(1, 0, At, B0); PG8_MMA(1, 1, At, B1); PG8_BAR; PG8_SCHED;
	s_setprio 0
	s_add_i32 s26, s44, s31
	v_lshl_add_u64 v[168:169], v[168:169], 0, s[70:71]
	s_mov_b32 m0, s26
	ds_read_b128 v[182:185], v197 offset:49152
	ds_read_b128 v[186:189], v197 offset:50176
	ds_read_b128 v[190:193], v197 offset:51200
	ds_read_b128 v[200:203], v197 offset:52224
	ds_read_b128 v[204:207], v197 offset:53248
	ds_read_b128 v[210:213], v197 offset:54272
	ds_read_b128 v[226:229], v197 offset:55296
	ds_read_b128 v[230:233], v197 offset:56320
	global_load_lds_dwordx4 v[168:169], off
	s_add_i32 m0, s26, 0x2000
	s_add_u32 s20, s20, 0x1fff80
	v_lshl_add_u64 v[168:169], v[214:215], 0, s[70:71]
	s_addc_u32 s21, s21, 0
	s_add_i32 s26, s46, s31
	global_load_lds_dwordx4 v[168:169], off
	v_lshl_add_u64 v[168:169], s[20:21], 0, v[128:129]
	s_mov_b32 m0, s26
	s_nop 0
	global_load_lds_dwordx4 v[168:169], off
	v_lshl_add_u64 v[168:169], s[20:21], 0, v[162:163]
	s_add_i32 m0, s26, 0x2000
	s_nop 0
	global_load_lds_dwordx4 v[168:169], off
	v_lshl_add_u64 v[168:169], v[234:235], 0, s[70:71]
	s_mov_b32 m0, s39
	s_nop 0
	global_load_lds_dwordx4 v[168:169], off
	v_lshl_add_u64 v[168:169], v[236:237], 0, s[70:71]
	s_mov_b32 m0, s40
	s_nop 0
	global_load_lds_dwordx4 v[168:169], off
	s_waitcnt vmcnt(8)
	s_waitcnt lgkmcnt(0)
	s_setprio 1
	s_barrier
	v_mfma_f32_16x16x32_bf16 v[60:63], v[124:127], v[182:185], v[60:63]
	v_mfma_f32_16x16x32_bf16 v[56:59], v[138:141], v[182:185], v[56:59]
	v_mfma_f32_16x16x32_bf16 v[44:47], v[124:127], v[190:193], v[44:47]
	v_mfma_f32_16x16x32_bf16 v[40:43], v[138:141], v[190:193], v[40:43]
	v_mfma_f32_16x16x32_bf16 v[28:31], v[124:127], v[204:207], v[28:31]
	v_mfma_f32_16x16x32_bf16 v[24:27], v[138:141], v[204:207], v[24:27]
	v_mfma_f32_16x16x32_bf16 v[12:15], v[124:127], v[226:229], v[12:15]
	v_mfma_f32_16x16x32_bf16 v[8:11], v[138:141], v[226:229], v[8:11]
	v_mfma_f32_16x16x32_bf16 v[60:63], v[134:137], v[186:189], v[60:63]
	v_mfma_f32_16x16x32_bf16 v[56:59], v[142:145], v[186:189], v[56:59]
	v_mfma_f32_16x16x32_bf16 v[44:47], v[134:137], v[200:203], v[44:47]
	v_mfma_f32_16x16x32_bf16 v[40:43], v[142:145], v[200:203], v[40:43]
	v_mfma_f32_16x16x32_bf16 v[28:31], v[134:137], v[210:213], v[28:31]
	v_mfma_f32_16x16x32_bf16 v[24:27], v[142:145], v[210:213], v[24:27]
	v_mfma_f32_16x16x32_bf16 v[12:15], v[134:137], v[230:233], v[12:15]
	v_mfma_f32_16x16x32_bf16 v[8:11], v[142:145], v[230:233], v[8:11]
	s_setprio 0
	s_setprio 1
	v_mfma_f32_16x16x32_bf16 v[52:55], v[146:149], v[182:185], v[52:55]
	v_mfma_f32_16x16x32_bf16 v[48:51], v[154:157], v[182:185], v[48:51]
	v_mfma_f32_16x16x32_bf16 v[36:39], v[146:149], v[190:193], v[36:39]
	v_mfma_f32_16x16x32_bf16 v[32:35], v[154:157], v[190:193], v[32:35]
	v_mfma_f32_16x16x32_bf16 v[20:23], v[146:149], v[204:207], v[20:23]
	v_mfma_f32_16x16x32_bf16 v[16:19], v[154:157], v[204:207], v[16:19]
	v_mfma_f32_16x16x32_bf16 v[4:7], v[146:149], v[226:229], v[4:7]
	v_mfma_f32_16x16x32_bf16 v[0:3], v[154:157], v[226:229], v[0:3]
	v_mfma_f32_16x16x32_bf16 v[52:55], v[150:153], v[186:189], v[52:55]
	v_mfma_f32_16x16x32_bf16 v[48:51], v[158:161], v[186:189], v[48:51]
	v_mfma_f32_16x16x32_bf16 v[36:39], v[150:153], v[200:203], v[36:39]
	v_mfma_f32_16x16x32_bf16 v[32:35], v[158:161], v[200:203], v[32:35]
	v_mfma_f32_16x16x32_bf16 v[20:23], v[150:153], v[210:213], v[20:23]
	v_mfma_f32_16x16x32_bf16 v[16:19], v[158:161], v[210:213], v[16:19]
	v_mfma_f32_16x16x32_bf16 v[4:7], v[150:153], v[230:233], v[4:7]
	v_mfma_f32_16x16x32_bf16 v[0:3], v[158:161], v[230:233], v[0:3]
	s_barrier
	s_setprio 0
	s_cmpk_gt_u32 s42, 0x7d
	s_mov_b32 s42, s43
	s_cbranch_scc1 .LBB0_659
